# E20: P12 KV+NSA-in epilogue hand-written (one dispatch per unit), on top of E19
# speedup vs baseline: 1.0284x; 1.0064x over previous
.LBB0_2768:
	ds_read_b128 v[148:151], v173
	ds_read_b128 v[152:155], v173 offset:1024
	ds_read_b128 v[156:159], v173 offset:2048
	ds_read_b128 v[160:163], v173 offset:3072
	s_add_u32 s8, s0, 0xfffc0080
	s_addc_u32 s9, s1, -1
	s_cmp_eq_u32 s24, 12
	s_cselect_b32 s11, s7, s9
	s_cselect_b32 s10, s12, s8
	s_cselect_b32 s9, s21, s19
	s_cselect_b32 s8, s20, s17
	v_lshl_add_u64 v[206:207], s[0:1], 0, v[140:141]
	s_add_i32 m0, s42, 0xc000
	ds_read_b128 v[164:167], v174
	ds_read_b128 v[168:171], v174 offset:1024
	ds_read_b128 v[182:185], v174 offset:2048
	ds_read_b128 v[186:189], v174 offset:3072
	ds_read_b128 v[190:193], v174 offset:4096
	ds_read_b128 v[194:197], v174 offset:5120
	ds_read_b128 v[198:201], v174 offset:6144
	ds_read_b128 v[202:205], v174 offset:7168
	global_load_lds_dwordx4 v[206:207], off
	v_lshl_add_u64 v[206:207], s[0:1], 0, v[142:143]
	s_add_i32 m0, s42, 0xe000
	s_nop 0
	global_load_lds_dwordx4 v[206:207], off
	s_waitcnt lgkmcnt(8)
	s_barrier
	s_waitcnt lgkmcnt(0)
	s_setprio 1
	s_waitcnt lgkmcnt(0)
	v_mfma_f32_16x16x32_bf16 v[126:129], v[148:151], v[164:167], v[126:129]
	v_mfma_f32_16x16x32_bf16 v[122:125], v[156:159], v[164:167], v[122:125]
	v_mfma_f32_16x16x32_bf16 v[110:113], v[148:151], v[182:185], v[110:113]
	v_mfma_f32_16x16x32_bf16 v[106:109], v[156:159], v[182:185], v[106:109]
	v_mfma_f32_16x16x32_bf16 v[94:97], v[148:151], v[190:193], v[94:97]
	v_mfma_f32_16x16x32_bf16 v[90:93], v[156:159], v[190:193], v[90:93]
	v_mfma_f32_16x16x32_bf16 v[78:81], v[148:151], v[198:201], v[78:81]
	v_mfma_f32_16x16x32_bf16 v[74:77], v[156:159], v[198:201], v[74:77]
	v_mfma_f32_16x16x32_bf16 v[126:129], v[152:155], v[168:171], v[126:129]
	v_mfma_f32_16x16x32_bf16 v[122:125], v[160:163], v[168:171], v[122:125]
	v_mfma_f32_16x16x32_bf16 v[110:113], v[152:155], v[186:189], v[110:113]
	v_mfma_f32_16x16x32_bf16 v[106:109], v[160:163], v[186:189], v[106:109]
	v_mfma_f32_16x16x32_bf16 v[94:97], v[152:155], v[194:197], v[94:97]
	v_mfma_f32_16x16x32_bf16 v[90:93], v[160:163], v[194:197], v[90:93]
	v_mfma_f32_16x16x32_bf16 v[78:81], v[152:155], v[202:205], v[78:81]
	v_mfma_f32_16x16x32_bf16 v[74:77], v[160:163], v[202:205], v[74:77]
	s_setprio 0
	s_barrier
	s_add_i32 s25, s52, s41
	v_lshl_add_u64 v[222:223], s[8:9], 0, v[130:131]
	s_mov_b32 m0, s25
	ds_read_b128 v[206:209], v175
	ds_read_b128 v[210:213], v175 offset:1024
	ds_read_b128 v[214:217], v175 offset:2048
	ds_read_b128 v[218:221], v175 offset:3072
	global_load_lds_dwordx4 v[222:223], off
	v_lshl_add_u64 v[224:225], s[8:9], 0, v[132:133]
	s_add_i32 m0, s25, 0x2000
	s_nop 0
	global_load_lds_dwordx4 v[224:225], off
	s_barrier
	s_waitcnt lgkmcnt(0)
	s_setprio 1
	s_waitcnt lgkmcnt(0)
	v_mfma_f32_16x16x32_bf16 v[118:121], v[206:209], v[164:167], v[118:121]
	v_mfma_f32_16x16x32_bf16 v[114:117], v[214:217], v[164:167], v[114:117]
	v_mfma_f32_16x16x32_bf16 v[102:105], v[206:209], v[182:185], v[102:105]
	v_mfma_f32_16x16x32_bf16 v[98:101], v[214:217], v[182:185], v[98:101]
	v_mfma_f32_16x16x32_bf16 v[86:89], v[206:209], v[190:193], v[86:89]
	v_mfma_f32_16x16x32_bf16 v[82:85], v[214:217], v[190:193], v[82:85]
	v_mfma_f32_16x16x32_bf16 v[70:73], v[206:209], v[198:201], v[70:73]
	v_mfma_f32_16x16x32_bf16 v[66:69], v[214:217], v[198:201], v[66:69]
	v_mfma_f32_16x16x32_bf16 v[118:121], v[210:213], v[168:171], v[118:121]
	v_mfma_f32_16x16x32_bf16 v[114:117], v[218:221], v[168:171], v[114:117]
	v_mfma_f32_16x16x32_bf16 v[102:105], v[210:213], v[186:189], v[102:105]
	v_mfma_f32_16x16x32_bf16 v[98:101], v[218:221], v[186:189], v[98:101]
	v_mfma_f32_16x16x32_bf16 v[86:89], v[210:213], v[194:197], v[86:89]
	v_mfma_f32_16x16x32_bf16 v[82:85], v[218:221], v[194:197], v[82:85]
	v_mfma_f32_16x16x32_bf16 v[70:73], v[210:213], v[202:205], v[70:73]
	v_mfma_f32_16x16x32_bf16 v[66:69], v[218:221], v[202:205], v[66:69]
	s_setprio 0
	s_mov_b32 m0, s42
	v_lshl_add_u64 v[228:229], s[10:11], 0, v[130:131]
	s_barrier
	ds_read_b128 v[164:167], v174 offset:16384
	ds_read_b128 v[168:171], v174 offset:17408
	ds_read_b128 v[182:185], v174 offset:18432
	ds_read_b128 v[186:189], v174 offset:19456
	ds_read_b128 v[190:193], v174 offset:20480
	ds_read_b128 v[194:197], v174 offset:21504
	ds_read_b128 v[198:201], v174 offset:22528
	ds_read_b128 v[202:205], v174 offset:23552
	global_load_lds_dwordx4 v[228:229], off
	v_lshl_add_u64 v[230:231], s[10:11], 0, v[132:133]
	s_mov_b32 m0, s43
	s_nop 0
	global_load_lds_dwordx4 v[230:231], off
	s_barrier
	s_waitcnt lgkmcnt(0)
	s_setprio 1
	s_waitcnt lgkmcnt(0)
	v_mfma_f32_16x16x32_bf16 v[62:65], v[148:151], v[164:167], v[62:65]
	v_mfma_f32_16x16x32_bf16 v[58:61], v[156:159], v[164:167], v[58:61]
	v_mfma_f32_16x16x32_bf16 v[46:49], v[148:151], v[182:185], v[46:49]
	v_mfma_f32_16x16x32_bf16 v[42:45], v[156:159], v[182:185], v[42:45]
	v_mfma_f32_16x16x32_bf16 v[30:33], v[148:151], v[190:193], v[30:33]
	v_mfma_f32_16x16x32_bf16 v[26:29], v[156:159], v[190:193], v[26:29]
	v_mfma_f32_16x16x32_bf16 v[14:17], v[148:151], v[198:201], v[14:17]
	v_mfma_f32_16x16x32_bf16 v[10:13], v[156:159], v[198:201], v[10:13]
	v_mfma_f32_16x16x32_bf16 v[62:65], v[152:155], v[168:171], v[62:65]
	v_mfma_f32_16x16x32_bf16 v[58:61], v[160:163], v[168:171], v[58:61]
	v_mfma_f32_16x16x32_bf16 v[46:49], v[152:155], v[186:189], v[46:49]
	v_mfma_f32_16x16x32_bf16 v[42:45], v[160:163], v[186:189], v[42:45]
	v_mfma_f32_16x16x32_bf16 v[30:33], v[152:155], v[194:197], v[30:33]
	v_mfma_f32_16x16x32_bf16 v[26:29], v[160:163], v[194:197], v[26:29]
	v_mfma_f32_16x16x32_bf16 v[14:17], v[152:155], v[202:205], v[14:17]
	v_mfma_f32_16x16x32_bf16 v[10:13], v[160:163], v[202:205], v[10:13]
	s_setprio 0
	s_barrier
	s_add_u32 s26, s8, 0x40000
	s_addc_u32 s27, s9, 0
	s_add_i32 s25, s53, s41
	v_lshl_add_u64 v[148:149], s[26:27], 0, v[130:131]
	s_mov_b32 m0, s25
	s_nop 0
	global_load_lds_dwordx4 v[148:149], off
	v_lshl_add_u64 v[148:149], s[26:27], 0, v[132:133]
	s_add_i32 m0, s25, 0x2000
	s_nop 0
	global_load_lds_dwordx4 v[148:149], off
	s_waitcnt vmcnt(6)
	s_barrier
	s_setprio 1
	v_mfma_f32_16x16x32_bf16 v[54:57], v[206:209], v[164:167], v[54:57]
	v_mfma_f32_16x16x32_bf16 v[50:53], v[214:217], v[164:167], v[50:53]
	v_mfma_f32_16x16x32_bf16 v[38:41], v[206:209], v[182:185], v[38:41]
	v_mfma_f32_16x16x32_bf16 v[34:37], v[214:217], v[182:185], v[34:37]
	v_mfma_f32_16x16x32_bf16 v[22:25], v[206:209], v[190:193], v[22:25]
	v_mfma_f32_16x16x32_bf16 v[18:21], v[214:217], v[190:193], v[18:21]
	v_mfma_f32_16x16x32_bf16 v[6:9], v[206:209], v[198:201], v[6:9]
	v_mfma_f32_16x16x32_bf16 v[2:5], v[214:217], v[198:201], v[2:5]
	v_mfma_f32_16x16x32_bf16 v[54:57], v[210:213], v[168:171], v[54:57]
	v_mfma_f32_16x16x32_bf16 v[50:53], v[218:221], v[168:171], v[50:53]
	v_mfma_f32_16x16x32_bf16 v[38:41], v[210:213], v[186:189], v[38:41]
	v_mfma_f32_16x16x32_bf16 v[34:37], v[218:221], v[186:189], v[34:37]
	v_mfma_f32_16x16x32_bf16 v[22:25], v[210:213], v[194:197], v[22:25]
	v_mfma_f32_16x16x32_bf16 v[18:21], v[218:221], v[194:197], v[18:21]
	v_mfma_f32_16x16x32_bf16 v[6:9], v[210:213], v[202:205], v[6:9]
	v_mfma_f32_16x16x32_bf16 v[2:5], v[218:221], v[202:205], v[2:5]
	s_setprio 0
	s_add_i32 s25, 0, 0x18000
	v_add_u32_e32 v134, s25, v172
	s_barrier
	ds_read_b128 v[148:151], v134
	ds_read_b128 v[152:155], v134 offset:1024
	ds_read_b128 v[156:159], v134 offset:2048
	ds_read_b128 v[160:163], v134 offset:3072
	s_add_u32 s10, s10, 0x40000
	s_addc_u32 s11, s11, 0
	s_mov_b32 m0, s44
	v_lshl_add_u64 v[206:207], s[10:11], 0, v[130:131]
	ds_read_b128 v[164:167], v174 offset:32768
	ds_read_b128 v[168:171], v174 offset:33792
	ds_read_b128 v[182:185], v174 offset:34816
	ds_read_b128 v[186:189], v174 offset:35840
	ds_read_b128 v[190:193], v174 offset:36864
	ds_read_b128 v[194:197], v174 offset:37888
	ds_read_b128 v[198:201], v174 offset:38912
	ds_read_b128 v[202:205], v174 offset:39936
	global_load_lds_dwordx4 v[206:207], off
	v_lshl_add_u64 v[206:207], s[10:11], 0, v[132:133]
	s_mov_b32 m0, s45
	s_nop 0
	global_load_lds_dwordx4 v[206:207], off
	s_waitcnt lgkmcnt(8)
	s_barrier
	s_waitcnt lgkmcnt(0)
	s_setprio 1
	s_waitcnt lgkmcnt(0)
	v_mfma_f32_16x16x32_bf16 v[126:129], v[148:151], v[164:167], v[126:129]
	v_mfma_f32_16x16x32_bf16 v[122:125], v[156:159], v[164:167], v[122:125]
	v_mfma_f32_16x16x32_bf16 v[110:113], v[148:151], v[182:185], v[110:113]
	v_mfma_f32_16x16x32_bf16 v[106:109], v[156:159], v[182:185], v[106:109]
	v_mfma_f32_16x16x32_bf16 v[94:97], v[148:151], v[190:193], v[94:97]
	v_mfma_f32_16x16x32_bf16 v[90:93], v[156:159], v[190:193], v[90:93]
	v_mfma_f32_16x16x32_bf16 v[78:81], v[148:151], v[198:201], v[78:81]
	v_mfma_f32_16x16x32_bf16 v[74:77], v[156:159], v[198:201], v[74:77]
	v_mfma_f32_16x16x32_bf16 v[126:129], v[152:155], v[168:171], v[126:129]
	v_mfma_f32_16x16x32_bf16 v[122:125], v[160:163], v[168:171], v[122:125]
	v_mfma_f32_16x16x32_bf16 v[110:113], v[152:155], v[186:189], v[110:113]
	v_mfma_f32_16x16x32_bf16 v[106:109], v[160:163], v[186:189], v[106:109]
	v_mfma_f32_16x16x32_bf16 v[94:97], v[152:155], v[194:197], v[94:97]
	v_mfma_f32_16x16x32_bf16 v[90:93], v[160:163], v[194:197], v[90:93]
	v_mfma_f32_16x16x32_bf16 v[78:81], v[152:155], v[202:205], v[78:81]
	v_mfma_f32_16x16x32_bf16 v[74:77], v[160:163], v[202:205], v[74:77]
	s_setprio 0
	s_barrier
	s_add_i32 s10, 0, 0x1c000
	s_add_i32 s11, s25, s41
	v_add_u32_e32 v134, s10, v172
	v_lshl_add_u64 v[222:223], v[222:223], 0, s[14:15]
	s_mov_b32 m0, s11
	ds_read_b128 v[206:209], v134
	ds_read_b128 v[210:213], v134 offset:1024
	ds_read_b128 v[214:217], v134 offset:2048
	ds_read_b128 v[218:221], v134 offset:3072
	global_load_lds_dwordx4 v[222:223], off
	v_lshl_add_u64 v[222:223], v[224:225], 0, s[14:15]
	s_add_i32 m0, s11, 0x2000
	s_nop 0
	global_load_lds_dwordx4 v[222:223], off
	s_barrier
	s_waitcnt lgkmcnt(0)
	s_setprio 1
	s_waitcnt lgkmcnt(0)
	v_mfma_f32_16x16x32_bf16 v[118:121], v[206:209], v[164:167], v[118:121]
	v_mfma_f32_16x16x32_bf16 v[114:117], v[214:217], v[164:167], v[114:117]
	v_mfma_f32_16x16x32_bf16 v[102:105], v[206:209], v[182:185], v[102:105]
	v_mfma_f32_16x16x32_bf16 v[98:101], v[214:217], v[182:185], v[98:101]
	v_mfma_f32_16x16x32_bf16 v[86:89], v[206:209], v[190:193], v[86:89]
	v_mfma_f32_16x16x32_bf16 v[82:85], v[214:217], v[190:193], v[82:85]
	v_mfma_f32_16x16x32_bf16 v[70:73], v[206:209], v[198:201], v[70:73]
	v_mfma_f32_16x16x32_bf16 v[66:69], v[214:217], v[198:201], v[66:69]
	v_mfma_f32_16x16x32_bf16 v[118:121], v[210:213], v[168:171], v[118:121]
	v_mfma_f32_16x16x32_bf16 v[114:117], v[218:221], v[168:171], v[114:117]
	v_mfma_f32_16x16x32_bf16 v[102:105], v[210:213], v[186:189], v[102:105]
	v_mfma_f32_16x16x32_bf16 v[98:101], v[218:221], v[186:189], v[98:101]
	v_mfma_f32_16x16x32_bf16 v[86:89], v[210:213], v[194:197], v[86:89]
	v_mfma_f32_16x16x32_bf16 v[82:85], v[218:221], v[194:197], v[82:85]
	v_mfma_f32_16x16x32_bf16 v[70:73], v[210:213], v[202:205], v[70:73]
	v_mfma_f32_16x16x32_bf16 v[66:69], v[218:221], v[202:205], v[66:69]
	s_setprio 0
	s_mov_b32 m0, s47
	v_lshl_add_u64 v[222:223], v[228:229], 0, s[14:15]
	s_barrier
	ds_read_b128 v[164:167], v174 offset:49152
	ds_read_b128 v[168:171], v174 offset:50176
	ds_read_b128 v[182:185], v174 offset:51200
	ds_read_b128 v[186:189], v174 offset:52224
	ds_read_b128 v[190:193], v174 offset:53248
	ds_read_b128 v[194:197], v174 offset:54272
	ds_read_b128 v[198:201], v174 offset:55296
	ds_read_b128 v[202:205], v174 offset:56320
	global_load_lds_dwordx4 v[222:223], off
	v_lshl_add_u64 v[222:223], v[230:231], 0, s[14:15]
	s_mov_b32 m0, s48
	s_nop 0
	global_load_lds_dwordx4 v[222:223], off
	s_barrier
	s_waitcnt lgkmcnt(0)
	s_setprio 1
	s_waitcnt lgkmcnt(0)
	v_mfma_f32_16x16x32_bf16 v[62:65], v[148:151], v[164:167], v[62:65]
	v_mfma_f32_16x16x32_bf16 v[58:61], v[156:159], v[164:167], v[58:61]
	v_mfma_f32_16x16x32_bf16 v[46:49], v[148:151], v[182:185], v[46:49]
	v_mfma_f32_16x16x32_bf16 v[42:45], v[156:159], v[182:185], v[42:45]
	v_mfma_f32_16x16x32_bf16 v[30:33], v[148:151], v[190:193], v[30:33]
	v_mfma_f32_16x16x32_bf16 v[26:29], v[156:159], v[190:193], v[26:29]
	v_mfma_f32_16x16x32_bf16 v[14:17], v[148:151], v[198:201], v[14:17]
	v_mfma_f32_16x16x32_bf16 v[10:13], v[156:159], v[198:201], v[10:13]
	v_mfma_f32_16x16x32_bf16 v[62:65], v[152:155], v[168:171], v[62:65]
	v_mfma_f32_16x16x32_bf16 v[58:61], v[160:163], v[168:171], v[58:61]
	v_mfma_f32_16x16x32_bf16 v[46:49], v[152:155], v[186:189], v[46:49]
	v_mfma_f32_16x16x32_bf16 v[42:45], v[160:163], v[186:189], v[42:45]
	v_mfma_f32_16x16x32_bf16 v[30:33], v[152:155], v[194:197], v[30:33]
	v_mfma_f32_16x16x32_bf16 v[26:29], v[160:163], v[194:197], v[26:29]
	v_mfma_f32_16x16x32_bf16 v[14:17], v[152:155], v[202:205], v[14:17]
	v_mfma_f32_16x16x32_bf16 v[10:13], v[160:163], v[202:205], v[10:13]
	s_setprio 0
	s_barrier
	s_add_u32 s8, s8, 0x40080
	s_addc_u32 s9, s9, 0
	s_add_i32 s10, s10, s41
	v_lshl_add_u64 v[148:149], s[8:9], 0, v[130:131]
	s_mov_b32 m0, s10
	s_nop 0
	global_load_lds_dwordx4 v[148:149], off
	v_lshl_add_u64 v[148:149], s[8:9], 0, v[132:133]
	s_add_i32 m0, s10, 0x2000
	s_nop 0
	global_load_lds_dwordx4 v[148:149], off
	s_waitcnt vmcnt(6)
	s_barrier
	s_setprio 1
	v_mfma_f32_16x16x32_bf16 v[54:57], v[206:209], v[164:167], v[54:57]
	v_mfma_f32_16x16x32_bf16 v[50:53], v[214:217], v[164:167], v[50:53]
	v_mfma_f32_16x16x32_bf16 v[38:41], v[206:209], v[182:185], v[38:41]
	v_mfma_f32_16x16x32_bf16 v[34:37], v[214:217], v[182:185], v[34:37]
	v_mfma_f32_16x16x32_bf16 v[22:25], v[206:209], v[190:193], v[22:25]
	v_mfma_f32_16x16x32_bf16 v[18:21], v[214:217], v[190:193], v[18:21]
	v_mfma_f32_16x16x32_bf16 v[6:9], v[206:209], v[198:201], v[6:9]
	v_mfma_f32_16x16x32_bf16 v[2:5], v[214:217], v[198:201], v[2:5]
	v_mfma_f32_16x16x32_bf16 v[54:57], v[210:213], v[168:171], v[54:57]
	v_mfma_f32_16x16x32_bf16 v[50:53], v[218:221], v[168:171], v[50:53]
	v_mfma_f32_16x16x32_bf16 v[38:41], v[210:213], v[186:189], v[38:41]
	v_mfma_f32_16x16x32_bf16 v[34:37], v[218:221], v[186:189], v[34:37]
	v_mfma_f32_16x16x32_bf16 v[22:25], v[210:213], v[194:197], v[22:25]
	v_mfma_f32_16x16x32_bf16 v[18:21], v[218:221], v[194:197], v[18:21]
	v_mfma_f32_16x16x32_bf16 v[6:9], v[210:213], v[202:205], v[6:9]
	v_mfma_f32_16x16x32_bf16 v[2:5], v[218:221], v[202:205], v[2:5]
	s_setprio 0
	s_add_i32 s24, s24, 2
	s_add_u32 s0, s0, 0x100
	s_addc_u32 s1, s1, 0
	s_add_u32 s17, s17, 0x100
	s_addc_u32 s19, s19, 0
	s_cmp_gt_u32 s24, 13
	s_barrier
	s_cbranch_scc0 .LBB0_2768
	s_mov_b64 s[30:31], exec
	s_load_dwordx8 s[80:87], s[78:79], 0x130
	s_load_dwordx4 s[88:91], s[78:79], 0x270
	s_load_dwordx2 s[92:93], s[78:79], 0x280
	s_load_dwordx2 s[94:95], s[78:79], 0x200
	s_load_dwordx2 s[64:65], s[78:79], 0x220
	s_load_dwordx2 s[66:67], s[78:79], 0x1e0
	v_and_b32_e32 v148, 15, v248
	v_bfe_u32 v149, v248, 8, 1
	v_bfe_u32 v150, v248, 6, 2
	v_bfe_u32 v151, v248, 4, 2
	v_lshlrev_b32_e32 v152, 5, v150
	v_lshl_or_b32 v152, v151, 2, v152
	v_lshl_add_u32 v153, v149, 6, v148
	s_lshl_b32 s0, s6, 8
	v_add_u32_e32 v154, s0, v153
	s_cmp_ge_u32 s28, 6
	s_cbranch_scc1 .Lmy_kn_nsa
	s_cmp_ge_u32 s6, 64
	s_cbranch_scc1 .Lmy_kn_smp
	s_cmp_ge_u32 s28, 4
	s_cbranch_scc1 .Lmy_kn_p_bf
	s_lshl_b32 s0, s28, 10
	v_lshlrev_b32_e32 v155, 12, v154
	v_lshl_add_u32 v155, v152, 2, v155
	v_add_u32_e32 v155, s0, v155
	s_waitcnt lgkmcnt(0)
	global_store_dwordx4 v155, v[126:129], s[80:81]
	global_store_dwordx4 v155, v[122:125], s[80:81] offset:64
	global_store_dwordx4 v155, v[118:121], s[80:81] offset:512
	global_store_dwordx4 v155, v[114:117], s[80:81] offset:576
	v_add_u32_e32 v134, 0x10000, v155
	global_store_dwordx4 v134, v[110:113], s[80:81]
	v_add_u32_e32 v134, 0x10040, v155
	global_store_dwordx4 v134, v[106:109], s[80:81]
	v_add_u32_e32 v134, 0x10200, v155
	global_store_dwordx4 v134, v[102:105], s[80:81]
	v_add_u32_e32 v134, 0x10240, v155
	global_store_dwordx4 v134, v[98:101], s[80:81]
	v_add_u32_e32 v134, 0x20000, v155
	global_store_dwordx4 v134, v[94:97], s[80:81]
	v_add_u32_e32 v134, 0x20040, v155
	global_store_dwordx4 v134, v[90:93], s[80:81]
	v_add_u32_e32 v134, 0x20200, v155
	global_store_dwordx4 v134, v[86:89], s[80:81]
	v_add_u32_e32 v134, 0x20240, v155
	global_store_dwordx4 v134, v[82:85], s[80:81]
	v_add_u32_e32 v134, 0x30000, v155
	global_store_dwordx4 v134, v[78:81], s[80:81]
	v_add_u32_e32 v134, 0x30040, v155
	global_store_dwordx4 v134, v[74:77], s[80:81]
	v_add_u32_e32 v134, 0x30200, v155
	global_store_dwordx4 v134, v[70:73], s[80:81]
	v_add_u32_e32 v134, 0x30240, v155
	global_store_dwordx4 v134, v[66:69], s[80:81]
	v_add_u32_e32 v134, 0x80000, v155
	global_store_dwordx4 v134, v[62:65], s[80:81]
	v_add_u32_e32 v134, 0x80040, v155
	global_store_dwordx4 v134, v[58:61], s[80:81]
	v_add_u32_e32 v134, 0x80200, v155
	global_store_dwordx4 v134, v[54:57], s[80:81]
	v_add_u32_e32 v134, 0x80240, v155
	global_store_dwordx4 v134, v[50:53], s[80:81]
	v_add_u32_e32 v134, 0x90000, v155
	global_store_dwordx4 v134, v[46:49], s[80:81]
	v_add_u32_e32 v134, 0x90040, v155
	global_store_dwordx4 v134, v[42:45], s[80:81]
	v_add_u32_e32 v134, 0x90200, v155
	global_store_dwordx4 v134, v[38:41], s[80:81]
	v_add_u32_e32 v134, 0x90240, v155
	global_store_dwordx4 v134, v[34:37], s[80:81]
	v_add_u32_e32 v134, 0xa0000, v155
	global_store_dwordx4 v134, v[30:33], s[80:81]
	v_add_u32_e32 v134, 0xa0040, v155
	global_store_dwordx4 v134, v[26:29], s[80:81]
	v_add_u32_e32 v134, 0xa0200, v155
	global_store_dwordx4 v134, v[22:25], s[80:81]
	v_add_u32_e32 v134, 0xa0240, v155
	global_store_dwordx4 v134, v[18:21], s[80:81]
	v_add_u32_e32 v134, 0xb0000, v155
	global_store_dwordx4 v134, v[14:17], s[80:81]
	v_add_u32_e32 v134, 0xb0040, v155
	global_store_dwordx4 v134, v[10:13], s[80:81]
	v_add_u32_e32 v134, 0xb0200, v155
	global_store_dwordx4 v134, v[6:9], s[80:81]
	v_add_u32_e32 v134, 0xb0240, v155
	global_store_dwordx4 v134, v[2:5], s[80:81]
.Lmy_kn_p_bf:
	s_waitcnt lgkmcnt(0)
	s_cmp_lt_u32 s28, 2
	s_cbranch_scc1 .Lmy_kn_p_acmp
	s_bitcmp1_b32 s28, 0
	s_cbranch_scc1 .Lmy_kn_p_vt
	s_lshl_b32 s0, s28, 9
	v_mul_u32_u24_e32 v156, 0xc00, v154
	v_lshl_add_u32 v156, v152, 1, v156
	v_add_u32_e32 v156, s0, v156
	v_cvt_pk_bf16_f32 v158, v126, v127
	v_cvt_pk_bf16_f32 v159, v128, v129
	global_store_dwordx2 v156, v[158:159], s[88:89]
	v_cvt_pk_bf16_f32 v160, v122, v123
	v_cvt_pk_bf16_f32 v161, v124, v125
	global_store_dwordx2 v156, v[160:161], s[88:89] offset:32
	v_cvt_pk_bf16_f32 v158, v118, v119
	v_cvt_pk_bf16_f32 v159, v120, v121
	global_store_dwordx2 v156, v[158:159], s[88:89] offset:256
	v_cvt_pk_bf16_f32 v160, v114, v115
	v_cvt_pk_bf16_f32 v161, v116, v117
	global_store_dwordx2 v156, v[160:161], s[88:89] offset:288
	v_cvt_pk_bf16_f32 v158, v110, v111
	v_cvt_pk_bf16_f32 v159, v112, v113
	v_add_u32_e32 v134, 0xc000, v156
	global_store_dwordx2 v134, v[158:159], s[88:89]
	v_cvt_pk_bf16_f32 v160, v106, v107
	v_cvt_pk_bf16_f32 v161, v108, v109
	v_add_u32_e32 v134, 0xc020, v156
	global_store_dwordx2 v134, v[160:161], s[88:89]
	v_cvt_pk_bf16_f32 v158, v102, v103
	v_cvt_pk_bf16_f32 v159, v104, v105
	v_add_u32_e32 v134, 0xc100, v156
	global_store_dwordx2 v134, v[158:159], s[88:89]
	v_cvt_pk_bf16_f32 v160, v98, v99
	v_cvt_pk_bf16_f32 v161, v100, v101
	v_add_u32_e32 v134, 0xc120, v156
	global_store_dwordx2 v134, v[160:161], s[88:89]
	v_cvt_pk_bf16_f32 v158, v94, v95
	v_cvt_pk_bf16_f32 v159, v96, v97
	v_add_u32_e32 v134, 0x18000, v156
	global_store_dwordx2 v134, v[158:159], s[88:89]
	v_cvt_pk_bf16_f32 v160, v90, v91
	v_cvt_pk_bf16_f32 v161, v92, v93
	v_add_u32_e32 v134, 0x18020, v156
	global_store_dwordx2 v134, v[160:161], s[88:89]
	v_cvt_pk_bf16_f32 v158, v86, v87
	v_cvt_pk_bf16_f32 v159, v88, v89
	v_add_u32_e32 v134, 0x18100, v156
	global_store_dwordx2 v134, v[158:159], s[88:89]
	v_cvt_pk_bf16_f32 v160, v82, v83
	v_cvt_pk_bf16_f32 v161, v84, v85
	v_add_u32_e32 v134, 0x18120, v156
	global_store_dwordx2 v134, v[160:161], s[88:89]
	v_cvt_pk_bf16_f32 v158, v78, v79
	v_cvt_pk_bf16_f32 v159, v80, v81
	v_add_u32_e32 v134, 0x24000, v156
	global_store_dwordx2 v134, v[158:159], s[88:89]
	v_cvt_pk_bf16_f32 v160, v74, v75
	v_cvt_pk_bf16_f32 v161, v76, v77
	v_add_u32_e32 v134, 0x24020, v156
	global_store_dwordx2 v134, v[160:161], s[88:89]
	v_cvt_pk_bf16_f32 v158, v70, v71
	v_cvt_pk_bf16_f32 v159, v72, v73
	v_add_u32_e32 v134, 0x24100, v156
	global_store_dwordx2 v134, v[158:159], s[88:89]
	v_cvt_pk_bf16_f32 v160, v66, v67
	v_cvt_pk_bf16_f32 v161, v68, v69
	v_add_u32_e32 v134, 0x24120, v156
	global_store_dwordx2 v134, v[160:161], s[88:89]
	v_cvt_pk_bf16_f32 v158, v62, v63
	v_cvt_pk_bf16_f32 v159, v64, v65
	v_add_u32_e32 v134, 0x60000, v156
	global_store_dwordx2 v134, v[158:159], s[88:89]
	v_cvt_pk_bf16_f32 v160, v58, v59
	v_cvt_pk_bf16_f32 v161, v60, v61
	v_add_u32_e32 v134, 0x60020, v156
	global_store_dwordx2 v134, v[160:161], s[88:89]
	v_cvt_pk_bf16_f32 v158, v54, v55
	v_cvt_pk_bf16_f32 v159, v56, v57
	v_add_u32_e32 v134, 0x60100, v156
	global_store_dwordx2 v134, v[158:159], s[88:89]
	v_cvt_pk_bf16_f32 v160, v50, v51
	v_cvt_pk_bf16_f32 v161, v52, v53
	v_add_u32_e32 v134, 0x60120, v156
	global_store_dwordx2 v134, v[160:161], s[88:89]
	v_cvt_pk_bf16_f32 v158, v46, v47
	v_cvt_pk_bf16_f32 v159, v48, v49
	v_add_u32_e32 v134, 0x6c000, v156
	global_store_dwordx2 v134, v[158:159], s[88:89]
	v_cvt_pk_bf16_f32 v160, v42, v43
	v_cvt_pk_bf16_f32 v161, v44, v45
	v_add_u32_e32 v134, 0x6c020, v156
	global_store_dwordx2 v134, v[160:161], s[88:89]
	v_cvt_pk_bf16_f32 v158, v38, v39
	v_cvt_pk_bf16_f32 v159, v40, v41
	v_add_u32_e32 v134, 0x6c100, v156
	global_store_dwordx2 v134, v[158:159], s[88:89]
	v_cvt_pk_bf16_f32 v160, v34, v35
	v_cvt_pk_bf16_f32 v161, v36, v37
	v_add_u32_e32 v134, 0x6c120, v156
	global_store_dwordx2 v134, v[160:161], s[88:89]
	v_cvt_pk_bf16_f32 v158, v30, v31
	v_cvt_pk_bf16_f32 v159, v32, v33
	v_add_u32_e32 v134, 0x78000, v156
	global_store_dwordx2 v134, v[158:159], s[88:89]
	v_cvt_pk_bf16_f32 v160, v26, v27
	v_cvt_pk_bf16_f32 v161, v28, v29
	v_add_u32_e32 v134, 0x78020, v156
	global_store_dwordx2 v134, v[160:161], s[88:89]
	v_cvt_pk_bf16_f32 v158, v22, v23
	v_cvt_pk_bf16_f32 v159, v24, v25
	v_add_u32_e32 v134, 0x78100, v156
	global_store_dwordx2 v134, v[158:159], s[88:89]
	v_cvt_pk_bf16_f32 v160, v18, v19
	v_cvt_pk_bf16_f32 v161, v20, v21
	v_add_u32_e32 v134, 0x78120, v156
	global_store_dwordx2 v134, v[160:161], s[88:89]
	v_cvt_pk_bf16_f32 v158, v14, v15
	v_cvt_pk_bf16_f32 v159, v16, v17
	v_add_u32_e32 v134, 0x84000, v156
	global_store_dwordx2 v134, v[158:159], s[88:89]
	v_cvt_pk_bf16_f32 v160, v10, v11
	v_cvt_pk_bf16_f32 v161, v12, v13
	v_add_u32_e32 v134, 0x84020, v156
	global_store_dwordx2 v134, v[160:161], s[88:89]
	v_cvt_pk_bf16_f32 v158, v6, v7
	v_cvt_pk_bf16_f32 v159, v8, v9
	v_add_u32_e32 v134, 0x84100, v156
	global_store_dwordx2 v134, v[158:159], s[88:89]
	v_cvt_pk_bf16_f32 v160, v2, v3
	v_cvt_pk_bf16_f32 v161, v4, v5
	v_add_u32_e32 v134, 0x84120, v156
	global_store_dwordx2 v134, v[160:161], s[88:89]
	s_branch .Lmy_kn_p_win
.Lmy_kn_p_acmp:
	s_mul_i32 s0, s28, 0x11000
	s_lshl_b32 s1, s6, 6
	s_add_u32 s0, s0, s1
	s_lshl_b32 s0, s0, 11
	v_lshrrev_b32_e32 v156, 1, v150
	v_lshl_add_u32 v156, v149, 4, v156
	v_lshlrev_b32_e32 v156, 11, v156
	v_and_b32_e32 v157, 1, v150
	v_lshlrev_b32_e32 v157, 5, v157
	v_lshl_or_b32 v157, v148, 6, v157
	v_lshl_or_b32 v157, v151, 2, v157
	v_lshl_add_u32 v156, v157, 1, v156
	v_add_u32_e32 v156, s0, v156
	v_cvt_pk_bf16_f32 v158, v126, v127
	v_cvt_pk_bf16_f32 v159, v128, v129
	global_store_dwordx2 v156, v[158:159], s[94:95]
	v_cvt_pk_bf16_f32 v160, v122, v123
	v_cvt_pk_bf16_f32 v161, v124, v125
	global_store_dwordx2 v156, v[160:161], s[94:95] offset:32
	v_cvt_pk_bf16_f32 v158, v118, v119
	v_cvt_pk_bf16_f32 v159, v120, v121
	v_add_u32_e32 v134, 0x1000, v156
	global_store_dwordx2 v134, v[158:159], s[94:95]
	v_cvt_pk_bf16_f32 v160, v114, v115
	v_cvt_pk_bf16_f32 v161, v116, v117
	v_add_u32_e32 v134, 0x1020, v156
	global_store_dwordx2 v134, v[160:161], s[94:95]
	v_cvt_pk_bf16_f32 v158, v110, v111
	v_cvt_pk_bf16_f32 v159, v112, v113
	v_add_u32_e32 v134, 0x2000, v156
	global_store_dwordx2 v134, v[158:159], s[94:95]
	v_cvt_pk_bf16_f32 v160, v106, v107
	v_cvt_pk_bf16_f32 v161, v108, v109
	v_add_u32_e32 v134, 0x2020, v156
	global_store_dwordx2 v134, v[160:161], s[94:95]
	v_cvt_pk_bf16_f32 v158, v102, v103
	v_cvt_pk_bf16_f32 v159, v104, v105
	v_add_u32_e32 v134, 0x3000, v156
	global_store_dwordx2 v134, v[158:159], s[94:95]
	v_cvt_pk_bf16_f32 v160, v98, v99
	v_cvt_pk_bf16_f32 v161, v100, v101
	v_add_u32_e32 v134, 0x3020, v156
	global_store_dwordx2 v134, v[160:161], s[94:95]
	v_cvt_pk_bf16_f32 v158, v94, v95
	v_cvt_pk_bf16_f32 v159, v96, v97
	v_add_u32_e32 v134, 0x4000, v156
	global_store_dwordx2 v134, v[158:159], s[94:95]
	v_cvt_pk_bf16_f32 v160, v90, v91
	v_cvt_pk_bf16_f32 v161, v92, v93
	v_add_u32_e32 v134, 0x4020, v156
	global_store_dwordx2 v134, v[160:161], s[94:95]
	v_cvt_pk_bf16_f32 v158, v86, v87
	v_cvt_pk_bf16_f32 v159, v88, v89
	v_add_u32_e32 v134, 0x5000, v156
	global_store_dwordx2 v134, v[158:159], s[94:95]
	v_cvt_pk_bf16_f32 v160, v82, v83
	v_cvt_pk_bf16_f32 v161, v84, v85
	v_add_u32_e32 v134, 0x5020, v156
	global_store_dwordx2 v134, v[160:161], s[94:95]
	v_cvt_pk_bf16_f32 v158, v78, v79
	v_cvt_pk_bf16_f32 v159, v80, v81
	v_add_u32_e32 v134, 0x6000, v156
	global_store_dwordx2 v134, v[158:159], s[94:95]
	v_cvt_pk_bf16_f32 v160, v74, v75
	v_cvt_pk_bf16_f32 v161, v76, v77
	v_add_u32_e32 v134, 0x6020, v156
	global_store_dwordx2 v134, v[160:161], s[94:95]
	v_cvt_pk_bf16_f32 v158, v70, v71
	v_cvt_pk_bf16_f32 v159, v72, v73
	v_add_u32_e32 v134, 0x7000, v156
	global_store_dwordx2 v134, v[158:159], s[94:95]
	v_cvt_pk_bf16_f32 v160, v66, v67
	v_cvt_pk_bf16_f32 v161, v68, v69
	v_add_u32_e32 v134, 0x7020, v156
	global_store_dwordx2 v134, v[160:161], s[94:95]
	v_cvt_pk_bf16_f32 v158, v62, v63
	v_cvt_pk_bf16_f32 v159, v64, v65
	v_add_u32_e32 v134, 0x10000, v156
	global_store_dwordx2 v134, v[158:159], s[94:95]
	v_cvt_pk_bf16_f32 v160, v58, v59
	v_cvt_pk_bf16_f32 v161, v60, v61
	v_add_u32_e32 v134, 0x10020, v156
	global_store_dwordx2 v134, v[160:161], s[94:95]
	v_cvt_pk_bf16_f32 v158, v54, v55
	v_cvt_pk_bf16_f32 v159, v56, v57
	v_add_u32_e32 v134, 0x11000, v156
	global_store_dwordx2 v134, v[158:159], s[94:95]
	v_cvt_pk_bf16_f32 v160, v50, v51
	v_cvt_pk_bf16_f32 v161, v52, v53
	v_add_u32_e32 v134, 0x11020, v156
	global_store_dwordx2 v134, v[160:161], s[94:95]
	v_cvt_pk_bf16_f32 v158, v46, v47
	v_cvt_pk_bf16_f32 v159, v48, v49
	v_add_u32_e32 v134, 0x12000, v156
	global_store_dwordx2 v134, v[158:159], s[94:95]
	v_cvt_pk_bf16_f32 v160, v42, v43
	v_cvt_pk_bf16_f32 v161, v44, v45
	v_add_u32_e32 v134, 0x12020, v156
	global_store_dwordx2 v134, v[160:161], s[94:95]
	v_cvt_pk_bf16_f32 v158, v38, v39
	v_cvt_pk_bf16_f32 v159, v40, v41
	v_add_u32_e32 v134, 0x13000, v156
	global_store_dwordx2 v134, v[158:159], s[94:95]
	v_cvt_pk_bf16_f32 v160, v34, v35
	v_cvt_pk_bf16_f32 v161, v36, v37
	v_add_u32_e32 v134, 0x13020, v156
	global_store_dwordx2 v134, v[160:161], s[94:95]
	v_cvt_pk_bf16_f32 v158, v30, v31
	v_cvt_pk_bf16_f32 v159, v32, v33
	v_add_u32_e32 v134, 0x14000, v156
	global_store_dwordx2 v134, v[158:159], s[94:95]
	v_cvt_pk_bf16_f32 v160, v26, v27
	v_cvt_pk_bf16_f32 v161, v28, v29
	v_add_u32_e32 v134, 0x14020, v156
	global_store_dwordx2 v134, v[160:161], s[94:95]
	v_cvt_pk_bf16_f32 v158, v22, v23
	v_cvt_pk_bf16_f32 v159, v24, v25
	v_add_u32_e32 v134, 0x15000, v156
	global_store_dwordx2 v134, v[158:159], s[94:95]
	v_cvt_pk_bf16_f32 v160, v18, v19
	v_cvt_pk_bf16_f32 v161, v20, v21
	v_add_u32_e32 v134, 0x15020, v156
	global_store_dwordx2 v134, v[160:161], s[94:95]
	v_cvt_pk_bf16_f32 v158, v14, v15
	v_cvt_pk_bf16_f32 v159, v16, v17
	v_add_u32_e32 v134, 0x16000, v156
	global_store_dwordx2 v134, v[158:159], s[94:95]
	v_cvt_pk_bf16_f32 v160, v10, v11
	v_cvt_pk_bf16_f32 v161, v12, v13
	v_add_u32_e32 v134, 0x16020, v156
	global_store_dwordx2 v134, v[160:161], s[94:95]
	v_cvt_pk_bf16_f32 v158, v6, v7
	v_cvt_pk_bf16_f32 v159, v8, v9
	v_add_u32_e32 v134, 0x17000, v156
	global_store_dwordx2 v134, v[158:159], s[94:95]
	v_cvt_pk_bf16_f32 v160, v2, v3
	v_cvt_pk_bf16_f32 v161, v4, v5
	v_add_u32_e32 v134, 0x17020, v156
	global_store_dwordx2 v134, v[160:161], s[94:95]
	s_branch .LBB0_2755
.Lmy_kn_p_vt:
	s_cmp_eq_u32 s28, 3
	s_cselect_b32 s24, s90, s92
	s_cselect_b32 s25, s91, s93
	s_add_u32 s26, s24, 0x1000
	s_addc_u32 s27, s25, 0
	s_add_u32 s34, s24, 0x2000
	s_addc_u32 s35, s25, 0
	s_add_u32 s36, s24, 0x3000
	s_addc_u32 s37, s25, 0
	s_lshr_b32 s0, s6, 3
	s_lshl_b32 s0, s0, 20
	s_and_b32 s1, s6, 7
	s_lshl_b32 s1, s1, 9
	s_add_u32 s0, s0, s1
	v_lshlrev_b32_e32 v156, 12, v152
	v_lshl_add_u32 v156, v153, 1, v156
	v_add_u32_e32 v156, s0, v156
	v_cvt_pk_bf16_f32 v158, v126, v127
	v_cvt_pk_bf16_f32 v159, v128, v129
	global_store_short v156, v158, s[24:25]
	global_store_short_d16_hi v156, v158, s[26:27]
	global_store_short v156, v159, s[34:35]
	global_store_short_d16_hi v156, v159, s[36:37]
	v_cvt_pk_bf16_f32 v160, v122, v123
	v_cvt_pk_bf16_f32 v161, v124, v125
	v_add_u32_e32 v134, 0x10000, v156
	global_store_short v134, v160, s[24:25]
	global_store_short_d16_hi v134, v160, s[26:27]
	global_store_short v134, v161, s[34:35]
	global_store_short_d16_hi v134, v161, s[36:37]
	v_cvt_pk_bf16_f32 v158, v118, v119
	v_cvt_pk_bf16_f32 v159, v120, v121
	v_add_u32_e32 v134, 0x80000, v156
	global_store_short v134, v158, s[24:25]
	global_store_short_d16_hi v134, v158, s[26:27]
	global_store_short v134, v159, s[34:35]
	global_store_short_d16_hi v134, v159, s[36:37]
	v_cvt_pk_bf16_f32 v160, v114, v115
	v_cvt_pk_bf16_f32 v161, v116, v117
	v_add_u32_e32 v134, 0x90000, v156
	global_store_short v134, v160, s[24:25]
	global_store_short_d16_hi v134, v160, s[26:27]
	global_store_short v134, v161, s[34:35]
	global_store_short_d16_hi v134, v161, s[36:37]
	v_cvt_pk_bf16_f32 v158, v110, v111
	v_cvt_pk_bf16_f32 v159, v112, v113
	global_store_short v156, v158, s[24:25] offset:32
	global_store_short_d16_hi v156, v158, s[26:27] offset:32
	global_store_short v156, v159, s[34:35] offset:32
	global_store_short_d16_hi v156, v159, s[36:37] offset:32
	v_cvt_pk_bf16_f32 v160, v106, v107
	v_cvt_pk_bf16_f32 v161, v108, v109
	v_add_u32_e32 v134, 0x10020, v156
	global_store_short v134, v160, s[24:25]
	global_store_short_d16_hi v134, v160, s[26:27]
	global_store_short v134, v161, s[34:35]
	global_store_short_d16_hi v134, v161, s[36:37]
	v_cvt_pk_bf16_f32 v158, v102, v103
	v_cvt_pk_bf16_f32 v159, v104, v105
	v_add_u32_e32 v134, 0x80020, v156
	global_store_short v134, v158, s[24:25]
	global_store_short_d16_hi v134, v158, s[26:27]
	global_store_short v134, v159, s[34:35]
	global_store_short_d16_hi v134, v159, s[36:37]
	v_cvt_pk_bf16_f32 v160, v98, v99
	v_cvt_pk_bf16_f32 v161, v100, v101
	v_add_u32_e32 v134, 0x90020, v156
	global_store_short v134, v160, s[24:25]
	global_store_short_d16_hi v134, v160, s[26:27]
	global_store_short v134, v161, s[34:35]
	global_store_short_d16_hi v134, v161, s[36:37]
	v_cvt_pk_bf16_f32 v158, v94, v95
	v_cvt_pk_bf16_f32 v159, v96, v97
	global_store_short v156, v158, s[24:25] offset:64
	global_store_short_d16_hi v156, v158, s[26:27] offset:64
	global_store_short v156, v159, s[34:35] offset:64
	global_store_short_d16_hi v156, v159, s[36:37] offset:64
	v_cvt_pk_bf16_f32 v160, v90, v91
	v_cvt_pk_bf16_f32 v161, v92, v93
	v_add_u32_e32 v134, 0x10040, v156
	global_store_short v134, v160, s[24:25]
	global_store_short_d16_hi v134, v160, s[26:27]
	global_store_short v134, v161, s[34:35]
	global_store_short_d16_hi v134, v161, s[36:37]
	v_cvt_pk_bf16_f32 v158, v86, v87
	v_cvt_pk_bf16_f32 v159, v88, v89
	v_add_u32_e32 v134, 0x80040, v156
	global_store_short v134, v158, s[24:25]
	global_store_short_d16_hi v134, v158, s[26:27]
	global_store_short v134, v159, s[34:35]
	global_store_short_d16_hi v134, v159, s[36:37]
	v_cvt_pk_bf16_f32 v160, v82, v83
	v_cvt_pk_bf16_f32 v161, v84, v85
	v_add_u32_e32 v134, 0x90040, v156
	global_store_short v134, v160, s[24:25]
	global_store_short_d16_hi v134, v160, s[26:27]
	global_store_short v134, v161, s[34:35]
	global_store_short_d16_hi v134, v161, s[36:37]
	v_cvt_pk_bf16_f32 v158, v78, v79
	v_cvt_pk_bf16_f32 v159, v80, v81
	global_store_short v156, v158, s[24:25] offset:96
	global_store_short_d16_hi v156, v158, s[26:27] offset:96
	global_store_short v156, v159, s[34:35] offset:96
	global_store_short_d16_hi v156, v159, s[36:37] offset:96
	v_cvt_pk_bf16_f32 v160, v74, v75
	v_cvt_pk_bf16_f32 v161, v76, v77
	v_add_u32_e32 v134, 0x10060, v156
	global_store_short v134, v160, s[24:25]
	global_store_short_d16_hi v134, v160, s[26:27]
	global_store_short v134, v161, s[34:35]
	global_store_short_d16_hi v134, v161, s[36:37]
	v_cvt_pk_bf16_f32 v158, v70, v71
	v_cvt_pk_bf16_f32 v159, v72, v73
	v_add_u32_e32 v134, 0x80060, v156
	global_store_short v134, v158, s[24:25]
	global_store_short_d16_hi v134, v158, s[26:27]
	global_store_short v134, v159, s[34:35]
	global_store_short_d16_hi v134, v159, s[36:37]
	v_cvt_pk_bf16_f32 v160, v66, v67
	v_cvt_pk_bf16_f32 v161, v68, v69
	v_add_u32_e32 v134, 0x90060, v156
	global_store_short v134, v160, s[24:25]
	global_store_short_d16_hi v134, v160, s[26:27]
	global_store_short v134, v161, s[34:35]
	global_store_short_d16_hi v134, v161, s[36:37]
	v_cvt_pk_bf16_f32 v158, v62, v63
	v_cvt_pk_bf16_f32 v159, v64, v65
	global_store_short v156, v158, s[24:25] offset:256
	global_store_short_d16_hi v156, v158, s[26:27] offset:256
	global_store_short v156, v159, s[34:35] offset:256
	global_store_short_d16_hi v156, v159, s[36:37] offset:256
	v_cvt_pk_bf16_f32 v160, v58, v59
	v_cvt_pk_bf16_f32 v161, v60, v61
	v_add_u32_e32 v134, 0x10100, v156
	global_store_short v134, v160, s[24:25]
	global_store_short_d16_hi v134, v160, s[26:27]
	global_store_short v134, v161, s[34:35]
	global_store_short_d16_hi v134, v161, s[36:37]
	v_cvt_pk_bf16_f32 v158, v54, v55
	v_cvt_pk_bf16_f32 v159, v56, v57
	v_add_u32_e32 v134, 0x80100, v156
	global_store_short v134, v158, s[24:25]
	global_store_short_d16_hi v134, v158, s[26:27]
	global_store_short v134, v159, s[34:35]
	global_store_short_d16_hi v134, v159, s[36:37]
	v_cvt_pk_bf16_f32 v160, v50, v51
	v_cvt_pk_bf16_f32 v161, v52, v53
	v_add_u32_e32 v134, 0x90100, v156
	global_store_short v134, v160, s[24:25]
	global_store_short_d16_hi v134, v160, s[26:27]
	global_store_short v134, v161, s[34:35]
	global_store_short_d16_hi v134, v161, s[36:37]
	v_cvt_pk_bf16_f32 v158, v46, v47
	v_cvt_pk_bf16_f32 v159, v48, v49
	global_store_short v156, v158, s[24:25] offset:288
	global_store_short_d16_hi v156, v158, s[26:27] offset:288
	global_store_short v156, v159, s[34:35] offset:288
	global_store_short_d16_hi v156, v159, s[36:37] offset:288
	v_cvt_pk_bf16_f32 v160, v42, v43
	v_cvt_pk_bf16_f32 v161, v44, v45
	v_add_u32_e32 v134, 0x10120, v156
	global_store_short v134, v160, s[24:25]
	global_store_short_d16_hi v134, v160, s[26:27]
	global_store_short v134, v161, s[34:35]
	global_store_short_d16_hi v134, v161, s[36:37]
	v_cvt_pk_bf16_f32 v158, v38, v39
	v_cvt_pk_bf16_f32 v159, v40, v41
	v_add_u32_e32 v134, 0x80120, v156
	global_store_short v134, v158, s[24:25]
	global_store_short_d16_hi v134, v158, s[26:27]
	global_store_short v134, v159, s[34:35]
	global_store_short_d16_hi v134, v159, s[36:37]
	v_cvt_pk_bf16_f32 v160, v34, v35
	v_cvt_pk_bf16_f32 v161, v36, v37
	v_add_u32_e32 v134, 0x90120, v156
	global_store_short v134, v160, s[24:25]
	global_store_short_d16_hi v134, v160, s[26:27]
	global_store_short v134, v161, s[34:35]
	global_store_short_d16_hi v134, v161, s[36:37]
	v_cvt_pk_bf16_f32 v158, v30, v31
	v_cvt_pk_bf16_f32 v159, v32, v33
	global_store_short v156, v158, s[24:25] offset:320
	global_store_short_d16_hi v156, v158, s[26:27] offset:320
	global_store_short v156, v159, s[34:35] offset:320
	global_store_short_d16_hi v156, v159, s[36:37] offset:320
	v_cvt_pk_bf16_f32 v160, v26, v27
	v_cvt_pk_bf16_f32 v161, v28, v29
	v_add_u32_e32 v134, 0x10140, v156
	global_store_short v134, v160, s[24:25]
	global_store_short_d16_hi v134, v160, s[26:27]
	global_store_short v134, v161, s[34:35]
	global_store_short_d16_hi v134, v161, s[36:37]
	v_cvt_pk_bf16_f32 v158, v22, v23
	v_cvt_pk_bf16_f32 v159, v24, v25
	v_add_u32_e32 v134, 0x80140, v156
	global_store_short v134, v158, s[24:25]
	global_store_short_d16_hi v134, v158, s[26:27]
	global_store_short v134, v159, s[34:35]
	global_store_short_d16_hi v134, v159, s[36:37]
	v_cvt_pk_bf16_f32 v160, v18, v19
	v_cvt_pk_bf16_f32 v161, v20, v21
	v_add_u32_e32 v134, 0x90140, v156
	global_store_short v134, v160, s[24:25]
	global_store_short_d16_hi v134, v160, s[26:27]
	global_store_short v134, v161, s[34:35]
	global_store_short_d16_hi v134, v161, s[36:37]
	v_cvt_pk_bf16_f32 v158, v14, v15
	v_cvt_pk_bf16_f32 v159, v16, v17
	global_store_short v156, v158, s[24:25] offset:352
	global_store_short_d16_hi v156, v158, s[26:27] offset:352
	global_store_short v156, v159, s[34:35] offset:352
	global_store_short_d16_hi v156, v159, s[36:37] offset:352
	v_cvt_pk_bf16_f32 v160, v10, v11
	v_cvt_pk_bf16_f32 v161, v12, v13
	v_add_u32_e32 v134, 0x10160, v156
	global_store_short v134, v160, s[24:25]
	global_store_short_d16_hi v134, v160, s[26:27]
	global_store_short v134, v161, s[34:35]
	global_store_short_d16_hi v134, v161, s[36:37]
	v_cvt_pk_bf16_f32 v158, v6, v7
	v_cvt_pk_bf16_f32 v159, v8, v9
	v_add_u32_e32 v134, 0x80160, v156
	global_store_short v134, v158, s[24:25]
	global_store_short_d16_hi v134, v158, s[26:27]
	global_store_short v134, v159, s[34:35]
	global_store_short_d16_hi v134, v159, s[36:37]
	v_cvt_pk_bf16_f32 v160, v2, v3
	v_cvt_pk_bf16_f32 v161, v4, v5
	v_add_u32_e32 v134, 0x90160, v156
	global_store_short v134, v160, s[24:25]
	global_store_short_d16_hi v134, v160, s[26:27]
	global_store_short v134, v161, s[34:35]
	global_store_short_d16_hi v134, v161, s[36:37]
.Lmy_kn_p_win:
	s_cmp_lt_u32 s28, 4
	s_cbranch_scc1 .LBB0_2755
	s_and_b32 s1, s6, 7
	s_cmp_lt_u32 s1, 6
	s_cbranch_scc1 .LBB0_2755
	s_sub_u32 s1, s1, 6
	s_lshl_b32 s1, s1, 8
	s_lshr_b32 s0, s6, 3
	s_lshl_b32 s0, s0, 9
	s_add_u32 s0, s0, s1
	s_lshl_b32 s0, s0, 11
	s_sub_u32 s1, s28, 4
	s_lshl_b32 s1, s1, 10
	s_add_u32 s0, s0, s1
	v_lshlrev_b32_e32 v155, 11, v153
	v_lshl_add_u32 v155, v152, 2, v155
	v_add_u32_e32 v155, s0, v155
	global_store_dwordx4 v155, v[126:129], s[84:85]
	global_store_dwordx4 v155, v[122:125], s[84:85] offset:64
	global_store_dwordx4 v155, v[118:121], s[84:85] offset:512
	global_store_dwordx4 v155, v[114:117], s[84:85] offset:576
	v_add_u32_e32 v134, 0x8000, v155
	global_store_dwordx4 v134, v[110:113], s[84:85]
	v_add_u32_e32 v134, 0x8040, v155
	global_store_dwordx4 v134, v[106:109], s[84:85]
	v_add_u32_e32 v134, 0x8200, v155
	global_store_dwordx4 v134, v[102:105], s[84:85]
	v_add_u32_e32 v134, 0x8240, v155
	global_store_dwordx4 v134, v[98:101], s[84:85]
	v_add_u32_e32 v134, 0x10000, v155
	global_store_dwordx4 v134, v[94:97], s[84:85]
	v_add_u32_e32 v134, 0x10040, v155
	global_store_dwordx4 v134, v[90:93], s[84:85]
	v_add_u32_e32 v134, 0x10200, v155
	global_store_dwordx4 v134, v[86:89], s[84:85]
	v_add_u32_e32 v134, 0x10240, v155
	global_store_dwordx4 v134, v[82:85], s[84:85]
	v_add_u32_e32 v134, 0x18000, v155
	global_store_dwordx4 v134, v[78:81], s[84:85]
	v_add_u32_e32 v134, 0x18040, v155
	global_store_dwordx4 v134, v[74:77], s[84:85]
	v_add_u32_e32 v134, 0x18200, v155
	global_store_dwordx4 v134, v[70:73], s[84:85]
	v_add_u32_e32 v134, 0x18240, v155
	global_store_dwordx4 v134, v[66:69], s[84:85]
	v_add_u32_e32 v134, 0x40000, v155
	global_store_dwordx4 v134, v[62:65], s[84:85]
	v_add_u32_e32 v134, 0x40040, v155
	global_store_dwordx4 v134, v[58:61], s[84:85]
	v_add_u32_e32 v134, 0x40200, v155
	global_store_dwordx4 v134, v[54:57], s[84:85]
	v_add_u32_e32 v134, 0x40240, v155
	global_store_dwordx4 v134, v[50:53], s[84:85]
	v_add_u32_e32 v134, 0x48000, v155
	global_store_dwordx4 v134, v[46:49], s[84:85]
	v_add_u32_e32 v134, 0x48040, v155
	global_store_dwordx4 v134, v[42:45], s[84:85]
	v_add_u32_e32 v134, 0x48200, v155
	global_store_dwordx4 v134, v[38:41], s[84:85]
	v_add_u32_e32 v134, 0x48240, v155
	global_store_dwordx4 v134, v[34:37], s[84:85]
	v_add_u32_e32 v134, 0x50000, v155
	global_store_dwordx4 v134, v[30:33], s[84:85]
	v_add_u32_e32 v134, 0x50040, v155
	global_store_dwordx4 v134, v[26:29], s[84:85]
	v_add_u32_e32 v134, 0x50200, v155
	global_store_dwordx4 v134, v[22:25], s[84:85]
	v_add_u32_e32 v134, 0x50240, v155
	global_store_dwordx4 v134, v[18:21], s[84:85]
	v_add_u32_e32 v134, 0x58000, v155
	global_store_dwordx4 v134, v[14:17], s[84:85]
	v_add_u32_e32 v134, 0x58040, v155
	global_store_dwordx4 v134, v[10:13], s[84:85]
	v_add_u32_e32 v134, 0x58200, v155
	global_store_dwordx4 v134, v[6:9], s[84:85]
	v_add_u32_e32 v134, 0x58240, v155
	global_store_dwordx4 v134, v[2:5], s[84:85]
	s_branch .LBB0_2755
.Lmy_kn_smp:
	s_sub_u32 s1, s6, 64
	s_cmp_ge_u32 s28, 4
	s_cbranch_scc1 .Lmy_kn_s_win
	s_lshl_b32 s1, s1, 20
	s_lshl_b32 s0, s28, 10
	s_add_u32 s0, s0, s1
	v_lshlrev_b32_e32 v155, 12, v153
	v_lshl_add_u32 v155, v152, 2, v155
	v_add_u32_e32 v155, s0, v155
	s_waitcnt lgkmcnt(0)
	global_store_dwordx4 v155, v[126:129], s[82:83]
	global_store_dwordx4 v155, v[122:125], s[82:83] offset:64
	global_store_dwordx4 v155, v[118:121], s[82:83] offset:512
	global_store_dwordx4 v155, v[114:117], s[82:83] offset:576
	v_add_u32_e32 v134, 0x10000, v155
	global_store_dwordx4 v134, v[110:113], s[82:83]
	v_add_u32_e32 v134, 0x10040, v155
	global_store_dwordx4 v134, v[106:109], s[82:83]
	v_add_u32_e32 v134, 0x10200, v155
	global_store_dwordx4 v134, v[102:105], s[82:83]
	v_add_u32_e32 v134, 0x10240, v155
	global_store_dwordx4 v134, v[98:101], s[82:83]
	v_add_u32_e32 v134, 0x20000, v155
	global_store_dwordx4 v134, v[94:97], s[82:83]
	v_add_u32_e32 v134, 0x20040, v155
	global_store_dwordx4 v134, v[90:93], s[82:83]
	v_add_u32_e32 v134, 0x20200, v155
	global_store_dwordx4 v134, v[86:89], s[82:83]
	v_add_u32_e32 v134, 0x20240, v155
	global_store_dwordx4 v134, v[82:85], s[82:83]
	v_add_u32_e32 v134, 0x30000, v155
	global_store_dwordx4 v134, v[78:81], s[82:83]
	v_add_u32_e32 v134, 0x30040, v155
	global_store_dwordx4 v134, v[74:77], s[82:83]
	v_add_u32_e32 v134, 0x30200, v155
	global_store_dwordx4 v134, v[70:73], s[82:83]
	v_add_u32_e32 v134, 0x30240, v155
	global_store_dwordx4 v134, v[66:69], s[82:83]
	v_add_u32_e32 v134, 0x80000, v155
	global_store_dwordx4 v134, v[62:65], s[82:83]
	v_add_u32_e32 v134, 0x80040, v155
	global_store_dwordx4 v134, v[58:61], s[82:83]
	v_add_u32_e32 v134, 0x80200, v155
	global_store_dwordx4 v134, v[54:57], s[82:83]
	v_add_u32_e32 v134, 0x80240, v155
	global_store_dwordx4 v134, v[50:53], s[82:83]
	v_add_u32_e32 v134, 0x90000, v155
	global_store_dwordx4 v134, v[46:49], s[82:83]
	v_add_u32_e32 v134, 0x90040, v155
	global_store_dwordx4 v134, v[42:45], s[82:83]
	v_add_u32_e32 v134, 0x90200, v155
	global_store_dwordx4 v134, v[38:41], s[82:83]
	v_add_u32_e32 v134, 0x90240, v155
	global_store_dwordx4 v134, v[34:37], s[82:83]
	v_add_u32_e32 v134, 0xa0000, v155
	global_store_dwordx4 v134, v[30:33], s[82:83]
	v_add_u32_e32 v134, 0xa0040, v155
	global_store_dwordx4 v134, v[26:29], s[82:83]
	v_add_u32_e32 v134, 0xa0200, v155
	global_store_dwordx4 v134, v[22:25], s[82:83]
	v_add_u32_e32 v134, 0xa0240, v155
	global_store_dwordx4 v134, v[18:21], s[82:83]
	v_add_u32_e32 v134, 0xb0000, v155
	global_store_dwordx4 v134, v[14:17], s[82:83]
	v_add_u32_e32 v134, 0xb0040, v155
	global_store_dwordx4 v134, v[10:13], s[82:83]
	v_add_u32_e32 v134, 0xb0200, v155
	global_store_dwordx4 v134, v[6:9], s[82:83]
	v_add_u32_e32 v134, 0xb0240, v155
	global_store_dwordx4 v134, v[2:5], s[82:83]
	s_branch .LBB0_2755
.Lmy_kn_s_win:
	s_lshl_b32 s1, s1, 14
	s_add_u32 s1, s1, 504
	s_lshl_b32 s1, s1, 11
	s_sub_u32 s0, s28, 4
	s_lshl_b32 s0, s0, 10
	s_add_u32 s0, s0, s1
	v_lshrrev_b32_e32 v155, 3, v148
	v_lshl_add_u32 v155, v149, 3, v155
	v_lshlrev_b32_e32 v155, 9, v155
	v_and_b32_e32 v156, 7, v148
	v_add_u32_e32 v155, v155, v156
	v_lshlrev_b32_e32 v155, 11, v155
	v_lshl_add_u32 v155, v152, 2, v155
	v_add_u32_e32 v155, s0, v155
	s_waitcnt lgkmcnt(0)
	global_store_dwordx4 v155, v[126:129], s[86:87]
	global_store_dwordx4 v155, v[122:125], s[86:87] offset:64
	global_store_dwordx4 v155, v[118:121], s[86:87] offset:512
	global_store_dwordx4 v155, v[114:117], s[86:87] offset:576
	v_add_u32_e32 v134, 0x200000, v155
	global_store_dwordx4 v134, v[110:113], s[86:87]
	v_add_u32_e32 v134, 0x200040, v155
	global_store_dwordx4 v134, v[106:109], s[86:87]
	v_add_u32_e32 v134, 0x200200, v155
	global_store_dwordx4 v134, v[102:105], s[86:87]
	v_add_u32_e32 v134, 0x200240, v155
	global_store_dwordx4 v134, v[98:101], s[86:87]
	v_add_u32_e32 v134, 0x400000, v155
	global_store_dwordx4 v134, v[94:97], s[86:87]
	v_add_u32_e32 v134, 0x400040, v155
	global_store_dwordx4 v134, v[90:93], s[86:87]
	v_add_u32_e32 v134, 0x400200, v155
	global_store_dwordx4 v134, v[86:89], s[86:87]
	v_add_u32_e32 v134, 0x400240, v155
	global_store_dwordx4 v134, v[82:85], s[86:87]
	v_add_u32_e32 v134, 0x600000, v155
	global_store_dwordx4 v134, v[78:81], s[86:87]
	v_add_u32_e32 v134, 0x600040, v155
	global_store_dwordx4 v134, v[74:77], s[86:87]
	v_add_u32_e32 v134, 0x600200, v155
	global_store_dwordx4 v134, v[70:73], s[86:87]
	v_add_u32_e32 v134, 0x600240, v155
	global_store_dwordx4 v134, v[66:69], s[86:87]
	v_add_u32_e32 v134, 0x1000000, v155
	global_store_dwordx4 v134, v[62:65], s[86:87]
	v_add_u32_e32 v134, 0x1000040, v155
	global_store_dwordx4 v134, v[58:61], s[86:87]
	v_add_u32_e32 v134, 0x1000200, v155
	global_store_dwordx4 v134, v[54:57], s[86:87]
	v_add_u32_e32 v134, 0x1000240, v155
	global_store_dwordx4 v134, v[50:53], s[86:87]
	v_add_u32_e32 v134, 0x1200000, v155
	global_store_dwordx4 v134, v[46:49], s[86:87]
	v_add_u32_e32 v134, 0x1200040, v155
	global_store_dwordx4 v134, v[42:45], s[86:87]
	v_add_u32_e32 v134, 0x1200200, v155
	global_store_dwordx4 v134, v[38:41], s[86:87]
	v_add_u32_e32 v134, 0x1200240, v155
	global_store_dwordx4 v134, v[34:37], s[86:87]
	v_add_u32_e32 v134, 0x1400000, v155
	global_store_dwordx4 v134, v[30:33], s[86:87]
	v_add_u32_e32 v134, 0x1400040, v155
	global_store_dwordx4 v134, v[26:29], s[86:87]
	v_add_u32_e32 v134, 0x1400200, v155
	global_store_dwordx4 v134, v[22:25], s[86:87]
	v_add_u32_e32 v134, 0x1400240, v155
	global_store_dwordx4 v134, v[18:21], s[86:87]
	v_add_u32_e32 v134, 0x1600000, v155
	global_store_dwordx4 v134, v[14:17], s[86:87]
	v_add_u32_e32 v134, 0x1600040, v155
	global_store_dwordx4 v134, v[10:13], s[86:87]
	v_add_u32_e32 v134, 0x1600200, v155
	global_store_dwordx4 v134, v[6:9], s[86:87]
	v_add_u32_e32 v134, 0x1600240, v155
	global_store_dwordx4 v134, v[2:5], s[86:87]
	s_branch .LBB0_2755
.Lmy_kn_nsa:
	s_cmp_eq_u32 s28, 10
	s_cbranch_scc1 .Lmy_kn_gate
	s_sub_u32 s0, s28, 6
	s_lshl_b32 s0, s0, 9
	v_lshlrev_b32_e32 v156, 11, v154
	v_lshl_add_u32 v156, v152, 1, v156
	v_add_u32_e32 v156, s0, v156
	s_waitcnt lgkmcnt(0)
	v_cvt_pk_bf16_f32 v158, v126, v127
	v_cvt_pk_bf16_f32 v159, v128, v129
	global_store_dwordx2 v156, v[158:159], s[64:65]
	v_cvt_pk_bf16_f32 v160, v122, v123
	v_cvt_pk_bf16_f32 v161, v124, v125
	global_store_dwordx2 v156, v[160:161], s[64:65] offset:32
	v_cvt_pk_bf16_f32 v158, v118, v119
	v_cvt_pk_bf16_f32 v159, v120, v121
	global_store_dwordx2 v156, v[158:159], s[64:65] offset:256
	v_cvt_pk_bf16_f32 v160, v114, v115
	v_cvt_pk_bf16_f32 v161, v116, v117
	global_store_dwordx2 v156, v[160:161], s[64:65] offset:288
	v_cvt_pk_bf16_f32 v158, v110, v111
	v_cvt_pk_bf16_f32 v159, v112, v113
	v_add_u32_e32 v134, 0x8000, v156
	global_store_dwordx2 v134, v[158:159], s[64:65]
	v_cvt_pk_bf16_f32 v160, v106, v107
	v_cvt_pk_bf16_f32 v161, v108, v109
	v_add_u32_e32 v134, 0x8020, v156
	global_store_dwordx2 v134, v[160:161], s[64:65]
	v_cvt_pk_bf16_f32 v158, v102, v103
	v_cvt_pk_bf16_f32 v159, v104, v105
	v_add_u32_e32 v134, 0x8100, v156
	global_store_dwordx2 v134, v[158:159], s[64:65]
	v_cvt_pk_bf16_f32 v160, v98, v99
	v_cvt_pk_bf16_f32 v161, v100, v101
	v_add_u32_e32 v134, 0x8120, v156
	global_store_dwordx2 v134, v[160:161], s[64:65]
	v_cvt_pk_bf16_f32 v158, v94, v95
	v_cvt_pk_bf16_f32 v159, v96, v97
	v_add_u32_e32 v134, 0x10000, v156
	global_store_dwordx2 v134, v[158:159], s[64:65]
	v_cvt_pk_bf16_f32 v160, v90, v91
	v_cvt_pk_bf16_f32 v161, v92, v93
	v_add_u32_e32 v134, 0x10020, v156
	global_store_dwordx2 v134, v[160:161], s[64:65]
	v_cvt_pk_bf16_f32 v158, v86, v87
	v_cvt_pk_bf16_f32 v159, v88, v89
	v_add_u32_e32 v134, 0x10100, v156
	global_store_dwordx2 v134, v[158:159], s[64:65]
	v_cvt_pk_bf16_f32 v160, v82, v83
	v_cvt_pk_bf16_f32 v161, v84, v85
	v_add_u32_e32 v134, 0x10120, v156
	global_store_dwordx2 v134, v[160:161], s[64:65]
	v_cvt_pk_bf16_f32 v158, v78, v79
	v_cvt_pk_bf16_f32 v159, v80, v81
	v_add_u32_e32 v134, 0x18000, v156
	global_store_dwordx2 v134, v[158:159], s[64:65]
	v_cvt_pk_bf16_f32 v160, v74, v75
	v_cvt_pk_bf16_f32 v161, v76, v77
	v_add_u32_e32 v134, 0x18020, v156
	global_store_dwordx2 v134, v[160:161], s[64:65]
	v_cvt_pk_bf16_f32 v158, v70, v71
	v_cvt_pk_bf16_f32 v159, v72, v73
	v_add_u32_e32 v134, 0x18100, v156
	global_store_dwordx2 v134, v[158:159], s[64:65]
	v_cvt_pk_bf16_f32 v160, v66, v67
	v_cvt_pk_bf16_f32 v161, v68, v69
	v_add_u32_e32 v134, 0x18120, v156
	global_store_dwordx2 v134, v[160:161], s[64:65]
	v_cvt_pk_bf16_f32 v158, v62, v63
	v_cvt_pk_bf16_f32 v159, v64, v65
	v_add_u32_e32 v134, 0x40000, v156
	global_store_dwordx2 v134, v[158:159], s[64:65]
	v_cvt_pk_bf16_f32 v160, v58, v59
	v_cvt_pk_bf16_f32 v161, v60, v61
	v_add_u32_e32 v134, 0x40020, v156
	global_store_dwordx2 v134, v[160:161], s[64:65]
	v_cvt_pk_bf16_f32 v158, v54, v55
	v_cvt_pk_bf16_f32 v159, v56, v57
	v_add_u32_e32 v134, 0x40100, v156
	global_store_dwordx2 v134, v[158:159], s[64:65]
	v_cvt_pk_bf16_f32 v160, v50, v51
	v_cvt_pk_bf16_f32 v161, v52, v53
	v_add_u32_e32 v134, 0x40120, v156
	global_store_dwordx2 v134, v[160:161], s[64:65]
	v_cvt_pk_bf16_f32 v158, v46, v47
	v_cvt_pk_bf16_f32 v159, v48, v49
	v_add_u32_e32 v134, 0x48000, v156
	global_store_dwordx2 v134, v[158:159], s[64:65]
	v_cvt_pk_bf16_f32 v160, v42, v43
	v_cvt_pk_bf16_f32 v161, v44, v45
	v_add_u32_e32 v134, 0x48020, v156
	global_store_dwordx2 v134, v[160:161], s[64:65]
	v_cvt_pk_bf16_f32 v158, v38, v39
	v_cvt_pk_bf16_f32 v159, v40, v41
	v_add_u32_e32 v134, 0x48100, v156
	global_store_dwordx2 v134, v[158:159], s[64:65]
	v_cvt_pk_bf16_f32 v160, v34, v35
	v_cvt_pk_bf16_f32 v161, v36, v37
	v_add_u32_e32 v134, 0x48120, v156
	global_store_dwordx2 v134, v[160:161], s[64:65]
	v_cvt_pk_bf16_f32 v158, v30, v31
	v_cvt_pk_bf16_f32 v159, v32, v33
	v_add_u32_e32 v134, 0x50000, v156
	global_store_dwordx2 v134, v[158:159], s[64:65]
	v_cvt_pk_bf16_f32 v160, v26, v27
	v_cvt_pk_bf16_f32 v161, v28, v29
	v_add_u32_e32 v134, 0x50020, v156
	global_store_dwordx2 v134, v[160:161], s[64:65]
	v_cvt_pk_bf16_f32 v158, v22, v23
	v_cvt_pk_bf16_f32 v159, v24, v25
	v_add_u32_e32 v134, 0x50100, v156
	global_store_dwordx2 v134, v[158:159], s[64:65]
	v_cvt_pk_bf16_f32 v160, v18, v19
	v_cvt_pk_bf16_f32 v161, v20, v21
	v_add_u32_e32 v134, 0x50120, v156
	global_store_dwordx2 v134, v[160:161], s[64:65]
	v_cvt_pk_bf16_f32 v158, v14, v15
	v_cvt_pk_bf16_f32 v159, v16, v17
	v_add_u32_e32 v134, 0x58000, v156
	global_store_dwordx2 v134, v[158:159], s[64:65]
	v_cvt_pk_bf16_f32 v160, v10, v11
	v_cvt_pk_bf16_f32 v161, v12, v13
	v_add_u32_e32 v134, 0x58020, v156
	global_store_dwordx2 v134, v[160:161], s[64:65]
	v_cvt_pk_bf16_f32 v158, v6, v7
	v_cvt_pk_bf16_f32 v159, v8, v9
	v_add_u32_e32 v134, 0x58100, v156
	global_store_dwordx2 v134, v[158:159], s[64:65]
	v_cvt_pk_bf16_f32 v160, v2, v3
	v_cvt_pk_bf16_f32 v161, v4, v5
	v_add_u32_e32 v134, 0x58120, v156
	global_store_dwordx2 v134, v[160:161], s[64:65]
	s_branch .LBB0_2755
.Lmy_kn_gate:
	v_readfirstlane_b32 s0, v150
	v_mul_u32_u24_e32 v156, 0xc0, v154
	v_lshl_add_u32 v156, v152, 2, v156
	s_waitcnt lgkmcnt(0)
	s_cmp_gt_u32 s0, 1
	s_cbranch_scc1 .LBB0_2755
	s_cmp_eq_u32 s0, 1
	s_cbranch_scc1 .Lmy_kn_gate1
	v_mul_f32_e32 v164, 0xbfb8aa3b, v126
	v_mul_f32_e32 v165, 0xbfb8aa3b, v127
	v_mul_f32_e32 v166, 0xbfb8aa3b, v128
	v_mul_f32_e32 v167, 0xbfb8aa3b, v129
	v_exp_f32_e32 v164, v164
	v_exp_f32_e32 v165, v165
	v_exp_f32_e32 v166, v166
	v_exp_f32_e32 v167, v167
	v_add_f32_e32 v164, 1.0, v164
	v_add_f32_e32 v165, 1.0, v165
	v_add_f32_e32 v166, 1.0, v166
	v_add_f32_e32 v167, 1.0, v167
	v_rcp_f32_e32 v164, v164
	v_rcp_f32_e32 v165, v165
	v_rcp_f32_e32 v166, v166
	v_rcp_f32_e32 v167, v167
	s_nop 1
	global_store_dwordx4 v156, v[164:167], s[66:67]
	v_mul_f32_e32 v168, 0xbfb8aa3b, v122
	v_mul_f32_e32 v169, 0xbfb8aa3b, v123
	v_mul_f32_e32 v170, 0xbfb8aa3b, v124
	v_mul_f32_e32 v171, 0xbfb8aa3b, v125
	v_exp_f32_e32 v168, v168
	v_exp_f32_e32 v169, v169
	v_exp_f32_e32 v170, v170
	v_exp_f32_e32 v171, v171
	v_add_f32_e32 v168, 1.0, v168
	v_add_f32_e32 v169, 1.0, v169
	v_add_f32_e32 v170, 1.0, v170
	v_add_f32_e32 v171, 1.0, v171
	v_rcp_f32_e32 v168, v168
	v_rcp_f32_e32 v169, v169
	v_rcp_f32_e32 v170, v170
	v_rcp_f32_e32 v171, v171
	s_nop 1
	global_store_dwordx4 v156, v[168:171], s[66:67] offset:64
	v_mul_f32_e32 v164, 0xbfb8aa3b, v110
	v_mul_f32_e32 v165, 0xbfb8aa3b, v111
	v_mul_f32_e32 v166, 0xbfb8aa3b, v112
	v_mul_f32_e32 v167, 0xbfb8aa3b, v113
	v_exp_f32_e32 v164, v164
	v_exp_f32_e32 v165, v165
	v_exp_f32_e32 v166, v166
	v_exp_f32_e32 v167, v167
	v_add_f32_e32 v164, 1.0, v164
	v_add_f32_e32 v165, 1.0, v165
	v_add_f32_e32 v166, 1.0, v166
	v_add_f32_e32 v167, 1.0, v167
	v_rcp_f32_e32 v164, v164
	v_rcp_f32_e32 v165, v165
	v_rcp_f32_e32 v166, v166
	v_rcp_f32_e32 v167, v167
	s_nop 1
	global_store_dwordx4 v156, v[164:167], s[66:67] offset:3072
	v_mul_f32_e32 v168, 0xbfb8aa3b, v106
	v_mul_f32_e32 v169, 0xbfb8aa3b, v107
	v_mul_f32_e32 v170, 0xbfb8aa3b, v108
	v_mul_f32_e32 v171, 0xbfb8aa3b, v109
	v_exp_f32_e32 v168, v168
	v_exp_f32_e32 v169, v169
	v_exp_f32_e32 v170, v170
	v_exp_f32_e32 v171, v171
	v_add_f32_e32 v168, 1.0, v168
	v_add_f32_e32 v169, 1.0, v169
	v_add_f32_e32 v170, 1.0, v170
	v_add_f32_e32 v171, 1.0, v171
	v_rcp_f32_e32 v168, v168
	v_rcp_f32_e32 v169, v169
	v_rcp_f32_e32 v170, v170
	v_rcp_f32_e32 v171, v171
	s_nop 1
	global_store_dwordx4 v156, v[168:171], s[66:67] offset:3136
	v_mul_f32_e32 v164, 0xbfb8aa3b, v94
	v_mul_f32_e32 v165, 0xbfb8aa3b, v95
	v_mul_f32_e32 v166, 0xbfb8aa3b, v96
	v_mul_f32_e32 v167, 0xbfb8aa3b, v97
	v_exp_f32_e32 v164, v164
	v_exp_f32_e32 v165, v165
	v_exp_f32_e32 v166, v166
	v_exp_f32_e32 v167, v167
	v_add_f32_e32 v164, 1.0, v164
	v_add_f32_e32 v165, 1.0, v165
	v_add_f32_e32 v166, 1.0, v166
	v_add_f32_e32 v167, 1.0, v167
	v_rcp_f32_e32 v164, v164
	v_rcp_f32_e32 v165, v165
	v_rcp_f32_e32 v166, v166
	v_rcp_f32_e32 v167, v167
	s_nop 1
	v_add_u32_e32 v134, 0x1800, v156
	global_store_dwordx4 v134, v[164:167], s[66:67]
	v_mul_f32_e32 v168, 0xbfb8aa3b, v90
	v_mul_f32_e32 v169, 0xbfb8aa3b, v91
	v_mul_f32_e32 v170, 0xbfb8aa3b, v92
	v_mul_f32_e32 v171, 0xbfb8aa3b, v93
	v_exp_f32_e32 v168, v168
	v_exp_f32_e32 v169, v169
	v_exp_f32_e32 v170, v170
	v_exp_f32_e32 v171, v171
	v_add_f32_e32 v168, 1.0, v168
	v_add_f32_e32 v169, 1.0, v169
	v_add_f32_e32 v170, 1.0, v170
	v_add_f32_e32 v171, 1.0, v171
	v_rcp_f32_e32 v168, v168
	v_rcp_f32_e32 v169, v169
	v_rcp_f32_e32 v170, v170
	v_rcp_f32_e32 v171, v171
	s_nop 1
	v_add_u32_e32 v134, 0x1840, v156
	global_store_dwordx4 v134, v[168:171], s[66:67]
	v_mul_f32_e32 v164, 0xbfb8aa3b, v78
	v_mul_f32_e32 v165, 0xbfb8aa3b, v79
	v_mul_f32_e32 v166, 0xbfb8aa3b, v80
	v_mul_f32_e32 v167, 0xbfb8aa3b, v81
	v_exp_f32_e32 v164, v164
	v_exp_f32_e32 v165, v165
	v_exp_f32_e32 v166, v166
	v_exp_f32_e32 v167, v167
	v_add_f32_e32 v164, 1.0, v164
	v_add_f32_e32 v165, 1.0, v165
	v_add_f32_e32 v166, 1.0, v166
	v_add_f32_e32 v167, 1.0, v167
	v_rcp_f32_e32 v164, v164
	v_rcp_f32_e32 v165, v165
	v_rcp_f32_e32 v166, v166
	v_rcp_f32_e32 v167, v167
	s_nop 1
	v_add_u32_e32 v134, 0x2400, v156
	global_store_dwordx4 v134, v[164:167], s[66:67]
	v_mul_f32_e32 v168, 0xbfb8aa3b, v74
	v_mul_f32_e32 v169, 0xbfb8aa3b, v75
	v_mul_f32_e32 v170, 0xbfb8aa3b, v76
	v_mul_f32_e32 v171, 0xbfb8aa3b, v77
	v_exp_f32_e32 v168, v168
	v_exp_f32_e32 v169, v169
	v_exp_f32_e32 v170, v170
	v_exp_f32_e32 v171, v171
	v_add_f32_e32 v168, 1.0, v168
	v_add_f32_e32 v169, 1.0, v169
	v_add_f32_e32 v170, 1.0, v170
	v_add_f32_e32 v171, 1.0, v171
	v_rcp_f32_e32 v168, v168
	v_rcp_f32_e32 v169, v169
	v_rcp_f32_e32 v170, v170
	v_rcp_f32_e32 v171, v171
	s_nop 1
	v_add_u32_e32 v134, 0x2440, v156
	global_store_dwordx4 v134, v[168:171], s[66:67]
	v_mul_f32_e32 v164, 0xbfb8aa3b, v62
	v_mul_f32_e32 v165, 0xbfb8aa3b, v63
	v_mul_f32_e32 v166, 0xbfb8aa3b, v64
	v_mul_f32_e32 v167, 0xbfb8aa3b, v65
	v_exp_f32_e32 v164, v164
	v_exp_f32_e32 v165, v165
	v_exp_f32_e32 v166, v166
	v_exp_f32_e32 v167, v167
	v_add_f32_e32 v164, 1.0, v164
	v_add_f32_e32 v165, 1.0, v165
	v_add_f32_e32 v166, 1.0, v166
	v_add_f32_e32 v167, 1.0, v167
	v_rcp_f32_e32 v164, v164
	v_rcp_f32_e32 v165, v165
	v_rcp_f32_e32 v166, v166
	v_rcp_f32_e32 v167, v167
	s_nop 1
	v_add_u32_e32 v134, 0x6000, v156
	global_store_dwordx4 v134, v[164:167], s[66:67]
	v_mul_f32_e32 v168, 0xbfb8aa3b, v58
	v_mul_f32_e32 v169, 0xbfb8aa3b, v59
	v_mul_f32_e32 v170, 0xbfb8aa3b, v60
	v_mul_f32_e32 v171, 0xbfb8aa3b, v61
	v_exp_f32_e32 v168, v168
	v_exp_f32_e32 v169, v169
	v_exp_f32_e32 v170, v170
	v_exp_f32_e32 v171, v171
	v_add_f32_e32 v168, 1.0, v168
	v_add_f32_e32 v169, 1.0, v169
	v_add_f32_e32 v170, 1.0, v170
	v_add_f32_e32 v171, 1.0, v171
	v_rcp_f32_e32 v168, v168
	v_rcp_f32_e32 v169, v169
	v_rcp_f32_e32 v170, v170
	v_rcp_f32_e32 v171, v171
	s_nop 1
	v_add_u32_e32 v134, 0x6040, v156
	global_store_dwordx4 v134, v[168:171], s[66:67]
	v_mul_f32_e32 v164, 0xbfb8aa3b, v46
	v_mul_f32_e32 v165, 0xbfb8aa3b, v47
	v_mul_f32_e32 v166, 0xbfb8aa3b, v48
	v_mul_f32_e32 v167, 0xbfb8aa3b, v49
	v_exp_f32_e32 v164, v164
	v_exp_f32_e32 v165, v165
	v_exp_f32_e32 v166, v166
	v_exp_f32_e32 v167, v167
	v_add_f32_e32 v164, 1.0, v164
	v_add_f32_e32 v165, 1.0, v165
	v_add_f32_e32 v166, 1.0, v166
	v_add_f32_e32 v167, 1.0, v167
	v_rcp_f32_e32 v164, v164
	v_rcp_f32_e32 v165, v165
	v_rcp_f32_e32 v166, v166
	v_rcp_f32_e32 v167, v167
	s_nop 1
	v_add_u32_e32 v134, 0x6c00, v156
	global_store_dwordx4 v134, v[164:167], s[66:67]
	v_mul_f32_e32 v168, 0xbfb8aa3b, v42
	v_mul_f32_e32 v169, 0xbfb8aa3b, v43
	v_mul_f32_e32 v170, 0xbfb8aa3b, v44
	v_mul_f32_e32 v171, 0xbfb8aa3b, v45
	v_exp_f32_e32 v168, v168
	v_exp_f32_e32 v169, v169
	v_exp_f32_e32 v170, v170
	v_exp_f32_e32 v171, v171
	v_add_f32_e32 v168, 1.0, v168
	v_add_f32_e32 v169, 1.0, v169
	v_add_f32_e32 v170, 1.0, v170
	v_add_f32_e32 v171, 1.0, v171
	v_rcp_f32_e32 v168, v168
	v_rcp_f32_e32 v169, v169
	v_rcp_f32_e32 v170, v170
	v_rcp_f32_e32 v171, v171
	s_nop 1
	v_add_u32_e32 v134, 0x6c40, v156
	global_store_dwordx4 v134, v[168:171], s[66:67]
	v_mul_f32_e32 v164, 0xbfb8aa3b, v30
	v_mul_f32_e32 v165, 0xbfb8aa3b, v31
	v_mul_f32_e32 v166, 0xbfb8aa3b, v32
	v_mul_f32_e32 v167, 0xbfb8aa3b, v33
	v_exp_f32_e32 v164, v164
	v_exp_f32_e32 v165, v165
	v_exp_f32_e32 v166, v166
	v_exp_f32_e32 v167, v167
	v_add_f32_e32 v164, 1.0, v164
	v_add_f32_e32 v165, 1.0, v165
	v_add_f32_e32 v166, 1.0, v166
	v_add_f32_e32 v167, 1.0, v167
	v_rcp_f32_e32 v164, v164
	v_rcp_f32_e32 v165, v165
	v_rcp_f32_e32 v166, v166
	v_rcp_f32_e32 v167, v167
	s_nop 1
	v_add_u32_e32 v134, 0x7800, v156
	global_store_dwordx4 v134, v[164:167], s[66:67]
	v_mul_f32_e32 v168, 0xbfb8aa3b, v26
	v_mul_f32_e32 v169, 0xbfb8aa3b, v27
	v_mul_f32_e32 v170, 0xbfb8aa3b, v28
	v_mul_f32_e32 v171, 0xbfb8aa3b, v29
	v_exp_f32_e32 v168, v168
	v_exp_f32_e32 v169, v169
	v_exp_f32_e32 v170, v170
	v_exp_f32_e32 v171, v171
	v_add_f32_e32 v168, 1.0, v168
	v_add_f32_e32 v169, 1.0, v169
	v_add_f32_e32 v170, 1.0, v170
	v_add_f32_e32 v171, 1.0, v171
	v_rcp_f32_e32 v168, v168
	v_rcp_f32_e32 v169, v169
	v_rcp_f32_e32 v170, v170
	v_rcp_f32_e32 v171, v171
	s_nop 1
	v_add_u32_e32 v134, 0x7840, v156
	global_store_dwordx4 v134, v[168:171], s[66:67]
	v_mul_f32_e32 v164, 0xbfb8aa3b, v14
	v_mul_f32_e32 v165, 0xbfb8aa3b, v15
	v_mul_f32_e32 v166, 0xbfb8aa3b, v16
	v_mul_f32_e32 v167, 0xbfb8aa3b, v17
	v_exp_f32_e32 v164, v164
	v_exp_f32_e32 v165, v165
	v_exp_f32_e32 v166, v166
	v_exp_f32_e32 v167, v167
	v_add_f32_e32 v164, 1.0, v164
	v_add_f32_e32 v165, 1.0, v165
	v_add_f32_e32 v166, 1.0, v166
	v_add_f32_e32 v167, 1.0, v167
	v_rcp_f32_e32 v164, v164
	v_rcp_f32_e32 v165, v165
	v_rcp_f32_e32 v166, v166
	v_rcp_f32_e32 v167, v167
	s_nop 1
	v_add_u32_e32 v134, 0x8400, v156
	global_store_dwordx4 v134, v[164:167], s[66:67]
	v_mul_f32_e32 v168, 0xbfb8aa3b, v10
	v_mul_f32_e32 v169, 0xbfb8aa3b, v11
	v_mul_f32_e32 v170, 0xbfb8aa3b, v12
	v_mul_f32_e32 v171, 0xbfb8aa3b, v13
	v_exp_f32_e32 v168, v168
	v_exp_f32_e32 v169, v169
	v_exp_f32_e32 v170, v170
	v_exp_f32_e32 v171, v171
	v_add_f32_e32 v168, 1.0, v168
	v_add_f32_e32 v169, 1.0, v169
	v_add_f32_e32 v170, 1.0, v170
	v_add_f32_e32 v171, 1.0, v171
	v_rcp_f32_e32 v168, v168
	v_rcp_f32_e32 v169, v169
	v_rcp_f32_e32 v170, v170
	v_rcp_f32_e32 v171, v171
	s_nop 1
	v_add_u32_e32 v134, 0x8440, v156
	global_store_dwordx4 v134, v[168:171], s[66:67]
	s_branch .LBB0_2755
.Lmy_kn_gate1:
	v_mul_f32_e32 v164, 0xbfb8aa3b, v126
	v_mul_f32_e32 v165, 0xbfb8aa3b, v127
	v_mul_f32_e32 v166, 0xbfb8aa3b, v128
	v_mul_f32_e32 v167, 0xbfb8aa3b, v129
	v_exp_f32_e32 v164, v164
	v_exp_f32_e32 v165, v165
	v_exp_f32_e32 v166, v166
	v_exp_f32_e32 v167, v167
	v_add_f32_e32 v164, 1.0, v164
	v_add_f32_e32 v165, 1.0, v165
	v_add_f32_e32 v166, 1.0, v166
	v_add_f32_e32 v167, 1.0, v167
	v_rcp_f32_e32 v164, v164
	v_rcp_f32_e32 v165, v165
	v_rcp_f32_e32 v166, v166
	v_rcp_f32_e32 v167, v167
	s_nop 1
	global_store_dwordx4 v156, v[164:167], s[66:67]
	v_mul_f32_e32 v168, 0xbfb8aa3b, v110
	v_mul_f32_e32 v169, 0xbfb8aa3b, v111
	v_mul_f32_e32 v170, 0xbfb8aa3b, v112
	v_mul_f32_e32 v171, 0xbfb8aa3b, v113
	v_exp_f32_e32 v168, v168
	v_exp_f32_e32 v169, v169
	v_exp_f32_e32 v170, v170
	v_exp_f32_e32 v171, v171
	v_add_f32_e32 v168, 1.0, v168
	v_add_f32_e32 v169, 1.0, v169
	v_add_f32_e32 v170, 1.0, v170
	v_add_f32_e32 v171, 1.0, v171
	v_rcp_f32_e32 v168, v168
	v_rcp_f32_e32 v169, v169
	v_rcp_f32_e32 v170, v170
	v_rcp_f32_e32 v171, v171
	s_nop 1
	global_store_dwordx4 v156, v[168:171], s[66:67] offset:3072
	v_mul_f32_e32 v164, 0xbfb8aa3b, v94
	v_mul_f32_e32 v165, 0xbfb8aa3b, v95
	v_mul_f32_e32 v166, 0xbfb8aa3b, v96
	v_mul_f32_e32 v167, 0xbfb8aa3b, v97
	v_exp_f32_e32 v164, v164
	v_exp_f32_e32 v165, v165
	v_exp_f32_e32 v166, v166
	v_exp_f32_e32 v167, v167
	v_add_f32_e32 v164, 1.0, v164
	v_add_f32_e32 v165, 1.0, v165
	v_add_f32_e32 v166, 1.0, v166
	v_add_f32_e32 v167, 1.0, v167
	v_rcp_f32_e32 v164, v164
	v_rcp_f32_e32 v165, v165
	v_rcp_f32_e32 v166, v166
	v_rcp_f32_e32 v167, v167
	s_nop 1
	v_add_u32_e32 v134, 0x1800, v156
	global_store_dwordx4 v134, v[164:167], s[66:67]
	v_mul_f32_e32 v168, 0xbfb8aa3b, v78
	v_mul_f32_e32 v169, 0xbfb8aa3b, v79
	v_mul_f32_e32 v170, 0xbfb8aa3b, v80
	v_mul_f32_e32 v171, 0xbfb8aa3b, v81
	v_exp_f32_e32 v168, v168
	v_exp_f32_e32 v169, v169
	v_exp_f32_e32 v170, v170
	v_exp_f32_e32 v171, v171
	v_add_f32_e32 v168, 1.0, v168
	v_add_f32_e32 v169, 1.0, v169
	v_add_f32_e32 v170, 1.0, v170
	v_add_f32_e32 v171, 1.0, v171
	v_rcp_f32_e32 v168, v168
	v_rcp_f32_e32 v169, v169
	v_rcp_f32_e32 v170, v170
	v_rcp_f32_e32 v171, v171
	s_nop 1
	v_add_u32_e32 v134, 0x2400, v156
	global_store_dwordx4 v134, v[168:171], s[66:67]
	v_mul_f32_e32 v164, 0xbfb8aa3b, v62
	v_mul_f32_e32 v165, 0xbfb8aa3b, v63
	v_mul_f32_e32 v166, 0xbfb8aa3b, v64
	v_mul_f32_e32 v167, 0xbfb8aa3b, v65
	v_exp_f32_e32 v164, v164
	v_exp_f32_e32 v165, v165
	v_exp_f32_e32 v166, v166
	v_exp_f32_e32 v167, v167
	v_add_f32_e32 v164, 1.0, v164
	v_add_f32_e32 v165, 1.0, v165
	v_add_f32_e32 v166, 1.0, v166
	v_add_f32_e32 v167, 1.0, v167
	v_rcp_f32_e32 v164, v164
	v_rcp_f32_e32 v165, v165
	v_rcp_f32_e32 v166, v166
	v_rcp_f32_e32 v167, v167
	s_nop 1
	v_add_u32_e32 v134, 0x6000, v156
	global_store_dwordx4 v134, v[164:167], s[66:67]
	v_mul_f32_e32 v168, 0xbfb8aa3b, v46
	v_mul_f32_e32 v169, 0xbfb8aa3b, v47
	v_mul_f32_e32 v170, 0xbfb8aa3b, v48
	v_mul_f32_e32 v171, 0xbfb8aa3b, v49
	v_exp_f32_e32 v168, v168
	v_exp_f32_e32 v169, v169
	v_exp_f32_e32 v170, v170
	v_exp_f32_e32 v171, v171
	v_add_f32_e32 v168, 1.0, v168
	v_add_f32_e32 v169, 1.0, v169
	v_add_f32_e32 v170, 1.0, v170
	v_add_f32_e32 v171, 1.0, v171
	v_rcp_f32_e32 v168, v168
	v_rcp_f32_e32 v169, v169
	v_rcp_f32_e32 v170, v170
	v_rcp_f32_e32 v171, v171
	s_nop 1
	v_add_u32_e32 v134, 0x6c00, v156
	global_store_dwordx4 v134, v[168:171], s[66:67]
	v_mul_f32_e32 v164, 0xbfb8aa3b, v30
	v_mul_f32_e32 v165, 0xbfb8aa3b, v31
	v_mul_f32_e32 v166, 0xbfb8aa3b, v32
	v_mul_f32_e32 v167, 0xbfb8aa3b, v33
	v_exp_f32_e32 v164, v164
	v_exp_f32_e32 v165, v165
	v_exp_f32_e32 v166, v166
	v_exp_f32_e32 v167, v167
	v_add_f32_e32 v164, 1.0, v164
	v_add_f32_e32 v165, 1.0, v165
	v_add_f32_e32 v166, 1.0, v166
	v_add_f32_e32 v167, 1.0, v167
	v_rcp_f32_e32 v164, v164
	v_rcp_f32_e32 v165, v165
	v_rcp_f32_e32 v166, v166
	v_rcp_f32_e32 v167, v167
	s_nop 1
	v_add_u32_e32 v134, 0x7800, v156
	global_store_dwordx4 v134, v[164:167], s[66:67]
	v_mul_f32_e32 v168, 0xbfb8aa3b, v14
	v_mul_f32_e32 v169, 0xbfb8aa3b, v15
	v_mul_f32_e32 v170, 0xbfb8aa3b, v16
	v_mul_f32_e32 v171, 0xbfb8aa3b, v17
	v_exp_f32_e32 v168, v168
	v_exp_f32_e32 v169, v169
	v_exp_f32_e32 v170, v170
	v_exp_f32_e32 v171, v171
	v_add_f32_e32 v168, 1.0, v168
	v_add_f32_e32 v169, 1.0, v169
	v_add_f32_e32 v170, 1.0, v170
	v_add_f32_e32 v171, 1.0, v171
	v_rcp_f32_e32 v168, v168
	v_rcp_f32_e32 v169, v169
	v_rcp_f32_e32 v170, v170
	v_rcp_f32_e32 v171, v171
	s_nop 1
	v_add_u32_e32 v134, 0x8400, v156
	global_store_dwordx4 v134, v[168:171], s[66:67]
	s_branch .LBB0_2755
